# MFMA order: accumulator pairs n-major with the token-row fragment order reversed in the second group (snake), otherwise as v61
# speedup vs baseline: 1.0898x; 1.0014x over previous
; #define PG8_STAGE(bufoff, gbase, voff) do { _Pragma("unroll") for (int _i = 0; _i < 2; ++_i) \
;         __builtin_amdgcn_global_load_lds((const unsigned*)((const char*)(gbase) + (voff)[_i]), (PG8_LAS unsigned*)(lds + (bufoff) + ldsw + _i * 8192), 16, 0, 0); } while (0)
; #define PG8_LDA(dst, b, h) do { _Pragma("unroll") for (int m = 0; m < 4; ++m) _Pragma("unroll") for (int k = 0; k < 2; ++k) dst[m][k] = *(const PG8_LAS bf16x8*)(lds + PG8_SA(b, h) + aoff + m * 2048 + k * 1024); } while (0)
; #define PG8_LDB(dst, b, h) do { _Pragma("unroll") for (int n = 0; n < 2; ++n) _Pragma("unroll") for (int k = 0; k < 2; ++k) dst[n][k] = *(const PG8_LAS bf16x8*)(lds + PG8_SB(b, h) + boff + n * 2048 + k * 1024); } while (0)
; #define PG8_WAIT_L(n) asm volatile("s_waitcnt lgkmcnt(" #n ")" ::: "memory")
; #define PG8_WAIT_V_SEL(sel) asm volatile("s_cmp_eq_u32 %0, 0\n\ts_cbranch_scc1 .Lw8_%=\n\ts_waitcnt vmcnt(22)\n\ts_branch .Lwd_%=\n.Lw8_%=:\n\ts_waitcnt vmcnt(8)\n.Lwd_%=:" :: "s"(sel) : "memory", "scc")
; #define PG8_BAR __builtin_amdgcn_s_barrier()
; #define PG8_SCHED __builtin_amdgcn_sched_barrier(0)
;     ...
;         for (int t = 0; t < nt * KREP; t += 2) {
;             const bool last = (t == nt * KREP - 2);
;             const int t1w = KREP > 1 ? ((t + 1) & (nt - 1)) : t + 1, t2w = KREP > 1 ? ((t + 2) & (nt - 1)) : t + 2;
;             const char* a1 = cA + (size_t)t1w * kstep;
;             const char* a2 = last ? nA : cA + (size_t)t2w * kstep; const char* b2 = last ? nB : cB + (size_t)t2w * kstep;
;             const char* a3 = a2 + kstep; const char* b3 = b2 + kstep;
;             if (last && has_next) S.a_ready(nxt);
;             const int relax = __builtin_amdgcn_readfirstlane((MK_RELAXW && t == 0 && ui > 0) ? 1 : 0);
;             if constexpr (SP2) {
;             PG8_LDB(B0, 0, 0); PG8_LDB(B1, 0, 1); PG8_SCHED; PG8_LDA(At, 0, 0); PG8_STAGE(PG8_SA(1, 1), a1 + hstep, voffA);
;             PG8_WAIT_V_SEL(relax);
;             PG8_WAIT_L(0); PG8_BAR; PG8_MMA(0, 0, At, B0); PG8_MMA(0, 1, At, B1); PG8_BAR; PG8_SCHED;
;             PG8_LDA(At, 0, 1); PG8_STAGE(PG8_SB(0, 0), b2, voffB); PG8_STAGE(PG8_SB(0, 1), b2 + hstep, voffB); PG8_STAGE(PG8_SA(0, 0), a2, voffA);
;             PG8_WAIT_V_SEL(relax);
;             PG8_WAIT_L(0); PG8_BAR; PG8_MMA(1, 0, At, B0); PG8_MMA(1, 1, At, B1); PG8_BAR; PG8_SCHED;
.LBB0_234:
	s_add_u32 s0, s78, 0xfff80080
	s_addc_u32 s1, s79, -1
	s_add_i32 s40, 0, 0x10000
	s_cmp_eq_u32 s37, 28
	s_cselect_b32 s83, s19, s1
	s_cselect_b32 s82, s20, s0
	s_cselect_b32 s81, s24, s35
	s_cselect_b32 s80, s31, s33
	s_add_i32 s41, 0, 0x14000
	ds_read_b128 v[142:145], v168
	ds_read_b128 v[146:149], v168 offset:1024
	ds_read_b128 v[150:153], v168 offset:2048
	ds_read_b128 v[154:157], v168 offset:3072
	ds_read_b128 v[158:161], v168 offset:16384
	ds_read_b128 v[162:165], v168 offset:17408
	ds_read_b128 v[174:177], v168 offset:18432
	ds_read_b128 v[188:191], v168 offset:19456
	s_add_i32 m0, s75, 0xc000
	ds_read_b128 v[198:201], v196
	ds_read_b128 v[202:205], v196 offset:1024
	ds_read_b128 v[206:209], v196 offset:2048
	ds_read_b128 v[210:213], v196 offset:3072
	ds_read_b128 v[214:217], v196 offset:4096
	ds_read_b128 v[218:221], v196 offset:5120
	ds_read_b128 v[222:225], v196 offset:6144
	ds_read_b128 v[226:229], v196 offset:7168
	global_load_lds_dwordx4 v138, s[78:79]
	s_add_i32 m0, s75, 0xe000
	s_nop 0
	global_load_lds_dwordx4 v140, s[78:79]
	s_waitcnt vmcnt(8)
	s_waitcnt lgkmcnt(0)
	s_setprio 1
	s_barrier
	v_mfma_f32_16x16x32_bf16 v[126:129], v[142:145], v[198:201], v[126:129]
	v_mfma_f32_16x16x32_bf16 v[126:129], v[146:149], v[202:205], v[126:129]
	v_mfma_f32_16x16x32_bf16 v[122:125], v[142:145], v[206:209], v[122:125]
	v_mfma_f32_16x16x32_bf16 v[122:125], v[146:149], v[210:213], v[122:125]
	v_mfma_f32_16x16x32_bf16 v[118:121], v[142:145], v[214:217], v[118:121]
	v_mfma_f32_16x16x32_bf16 v[118:121], v[146:149], v[218:221], v[118:121]
	v_mfma_f32_16x16x32_bf16 v[114:117], v[142:145], v[222:225], v[114:117]
	v_mfma_f32_16x16x32_bf16 v[114:117], v[146:149], v[226:229], v[114:117]
	v_mfma_f32_16x16x32_bf16 v[98:101], v[150:153], v[222:225], v[98:101]
	v_mfma_f32_16x16x32_bf16 v[98:101], v[154:157], v[226:229], v[98:101]
	v_mfma_f32_16x16x32_bf16 v[102:105], v[150:153], v[214:217], v[102:105]
	v_mfma_f32_16x16x32_bf16 v[102:105], v[154:157], v[218:221], v[102:105]
	v_mfma_f32_16x16x32_bf16 v[106:109], v[150:153], v[206:209], v[106:109]
	v_mfma_f32_16x16x32_bf16 v[106:109], v[154:157], v[210:213], v[106:109]
	v_mfma_f32_16x16x32_bf16 v[110:113], v[150:153], v[198:201], v[110:113]
	v_mfma_f32_16x16x32_bf16 v[110:113], v[154:157], v[202:205], v[110:113]
	v_mfma_f32_16x16x32_bf16 v[82:85], v[158:161], v[198:201], v[82:85]
	v_mfma_f32_16x16x32_bf16 v[82:85], v[162:165], v[202:205], v[82:85]
	v_mfma_f32_16x16x32_bf16 v[70:73], v[158:161], v[206:209], v[70:73]
	v_mfma_f32_16x16x32_bf16 v[70:73], v[162:165], v[210:213], v[70:73]
	v_mfma_f32_16x16x32_bf16 v[66:69], v[158:161], v[214:217], v[66:69]
	v_mfma_f32_16x16x32_bf16 v[66:69], v[162:165], v[218:221], v[66:69]
	v_mfma_f32_16x16x32_bf16 v[58:61], v[158:161], v[222:225], v[58:61]
	v_mfma_f32_16x16x32_bf16 v[58:61], v[162:165], v[226:229], v[58:61]
	v_mfma_f32_16x16x32_bf16 v[18:21], v[174:177], v[222:225], v[18:21]
	v_mfma_f32_16x16x32_bf16 v[18:21], v[188:191], v[226:229], v[18:21]
	v_mfma_f32_16x16x32_bf16 v[22:25], v[174:177], v[214:217], v[22:25]
	v_mfma_f32_16x16x32_bf16 v[22:25], v[188:191], v[218:221], v[22:25]
	v_mfma_f32_16x16x32_bf16 v[26:29], v[174:177], v[206:209], v[26:29]
	v_mfma_f32_16x16x32_bf16 v[26:29], v[188:191], v[210:213], v[26:29]
	v_mfma_f32_16x16x32_bf16 v[30:33], v[174:177], v[198:201], v[30:33]
	v_mfma_f32_16x16x32_bf16 v[30:33], v[188:191], v[202:205], v[30:33]
	s_barrier
	s_setprio 0
	s_add_i32 s0, s40, s87
	s_mov_b32 m0, s0
	ds_read_b128 v[198:201], v196 offset:16384
	ds_read_b128 v[202:205], v196 offset:17408
	ds_read_b128 v[206:209], v196 offset:18432
	ds_read_b128 v[210:213], v196 offset:19456
	ds_read_b128 v[214:217], v196 offset:20480
	ds_read_b128 v[218:221], v196 offset:21504
	ds_read_b128 v[222:225], v196 offset:22528
	ds_read_b128 v[226:229], v196 offset:23552
	global_load_lds_dwordx4 v182, s[80:81]
	s_add_i32 m0, s0, 0x2000
	s_add_u32 s0, s80, 0x80000
	s_addc_u32 s1, s81, 0
	s_add_i32 s40, s41, s87
	global_load_lds_dwordx4 v134, s[80:81]
	s_mov_b32 m0, s40
	s_nop 0
	global_load_lds_dwordx4 v182, s[0:1]
	s_add_i32 m0, s40, 0x2000
	s_nop 0
	global_load_lds_dwordx4 v134, s[0:1]
	s_mov_b32 m0, s75
	s_nop 0
	global_load_lds_dwordx4 v130, s[82:83]
	s_mov_b32 m0, s88
	s_nop 0
	global_load_lds_dwordx4 v132, s[82:83]
	s_waitcnt vmcnt(8)
	s_waitcnt lgkmcnt(0)
	s_setprio 1
	s_barrier
	v_mfma_f32_16x16x32_bf16 v[94:97], v[142:145], v[198:201], v[94:97]
	v_mfma_f32_16x16x32_bf16 v[94:97], v[146:149], v[202:205], v[94:97]
	v_mfma_f32_16x16x32_bf16 v[90:93], v[142:145], v[206:209], v[90:93]
	v_mfma_f32_16x16x32_bf16 v[90:93], v[146:149], v[210:213], v[90:93]
	v_mfma_f32_16x16x32_bf16 v[86:89], v[142:145], v[214:217], v[86:89]
	v_mfma_f32_16x16x32_bf16 v[86:89], v[146:149], v[218:221], v[86:89]
	v_mfma_f32_16x16x32_bf16 v[78:81], v[142:145], v[222:225], v[78:81]
	v_mfma_f32_16x16x32_bf16 v[78:81], v[146:149], v[226:229], v[78:81]
	v_mfma_f32_16x16x32_bf16 v[50:53], v[150:153], v[222:225], v[50:53]
	v_mfma_f32_16x16x32_bf16 v[50:53], v[154:157], v[226:229], v[50:53]
	v_mfma_f32_16x16x32_bf16 v[54:57], v[150:153], v[214:217], v[54:57]
	v_mfma_f32_16x16x32_bf16 v[54:57], v[154:157], v[218:221], v[54:57]
	v_mfma_f32_16x16x32_bf16 v[62:65], v[150:153], v[206:209], v[62:65]
	v_mfma_f32_16x16x32_bf16 v[62:65], v[154:157], v[210:213], v[62:65]
	v_mfma_f32_16x16x32_bf16 v[74:77], v[150:153], v[198:201], v[74:77]
	v_mfma_f32_16x16x32_bf16 v[74:77], v[154:157], v[202:205], v[74:77]
	v_mfma_f32_16x16x32_bf16 v[46:49], v[158:161], v[198:201], v[46:49]
	v_mfma_f32_16x16x32_bf16 v[46:49], v[162:165], v[202:205], v[46:49]
	v_mfma_f32_16x16x32_bf16 v[42:45], v[158:161], v[206:209], v[42:45]
	v_mfma_f32_16x16x32_bf16 v[42:45], v[162:165], v[210:213], v[42:45]
	v_mfma_f32_16x16x32_bf16 v[38:41], v[158:161], v[214:217], v[38:41]
	v_mfma_f32_16x16x32_bf16 v[38:41], v[162:165], v[218:221], v[38:41]
	v_mfma_f32_16x16x32_bf16 v[34:37], v[158:161], v[222:225], v[34:37]
	v_mfma_f32_16x16x32_bf16 v[34:37], v[162:165], v[226:229], v[34:37]
	v_mfma_f32_16x16x32_bf16 v[2:5], v[174:177], v[222:225], v[2:5]
	v_mfma_f32_16x16x32_bf16 v[2:5], v[188:191], v[226:229], v[2:5]
	v_mfma_f32_16x16x32_bf16 v[6:9], v[174:177], v[214:217], v[6:9]
	v_mfma_f32_16x16x32_bf16 v[6:9], v[188:191], v[218:221], v[6:9]
	v_mfma_f32_16x16x32_bf16 v[10:13], v[174:177], v[206:209], v[10:13]
	v_mfma_f32_16x16x32_bf16 v[10:13], v[188:191], v[210:213], v[10:13]
	v_mfma_f32_16x16x32_bf16 v[14:17], v[174:177], v[198:201], v[14:17]
	v_mfma_f32_16x16x32_bf16 v[14:17], v[188:191], v[202:205], v[14:17]
	s_barrier
; #define PG8_STAGE(bufoff, gbase, voff) do { _Pragma("unroll") for (int _i = 0; _i < 2; ++_i) \
;         __builtin_amdgcn_global_load_lds((const unsigned*)((const char*)(gbase) + (voff)[_i]), (PG8_LAS unsigned*)(lds + (bufoff) + ldsw + _i * 8192), 16, 0, 0); } while (0)
; #define PG8_LDA(dst, b, h) do { _Pragma("unroll") for (int m = 0; m < 4; ++m) _Pragma("unroll") for (int k = 0; k < 2; ++k) dst[m][k] = *(const PG8_LAS bf16x8*)(lds + PG8_SA(b, h) + aoff + m * 2048 + k * 1024); } while (0)
; #define PG8_LDB(dst, b, h) do { _Pragma("unroll") for (int n = 0; n < 2; ++n) _Pragma("unroll") for (int k = 0; k < 2; ++k) dst[n][k] = *(const PG8_LAS bf16x8*)(lds + PG8_SB(b, h) + boff + n * 2048 + k * 1024); } while (0)
; #define PG8_WAIT_V(n) asm volatile("s_waitcnt vmcnt(" #n ")" ::: "memory")
; #define PG8_WAIT_L(n) asm volatile("s_waitcnt lgkmcnt(" #n ")" ::: "memory")
; #define PG8_BAR __builtin_amdgcn_s_barrier()
; #define PG8_SCHED __builtin_amdgcn_sched_barrier(0)
;     ...
;             PG8_LDB(B0, 1, 0); PG8_LDB(B1, 1, 1); PG8_SCHED; PG8_LDA(At, 1, 0); PG8_STAGE(PG8_SA(0, 1), a2 + hstep, voffA);
;             PG8_WAIT_V(8); PG8_WAIT_L(0); PG8_BAR; PG8_MMA(0, 0, At, B0); PG8_MMA(0, 1, At, B1); PG8_BAR; PG8_SCHED;
;             PG8_LDA(At, 1, 1); PG8_STAGE(PG8_SB(1, 0), b3, voffB); PG8_STAGE(PG8_SB(1, 1), b3 + hstep, voffB); PG8_STAGE(PG8_SA(1, 0), a3, voffA);
;             PG8_WAIT_V(8); PG8_WAIT_L(0); PG8_BAR; PG8_MMA(1, 0, At, B0); PG8_MMA(1, 1, At, B1); PG8_BAR; PG8_SCHED;
;     ...
;         if constexpr (ALIGN_EPI) { if (wr == 0) PG8_BAR; }
	s_setprio 0
	s_add_i32 s40, 0, 0x18000
	s_add_i32 s41, 0, 0x1c000
	ds_read_b128 v[142:145], v168 offset:32768
	ds_read_b128 v[146:149], v168 offset:33792
	ds_read_b128 v[150:153], v168 offset:34816
	ds_read_b128 v[154:157], v168 offset:35840
	ds_read_b128 v[158:161], v168 offset:49152
	ds_read_b128 v[162:165], v168 offset:50176
	ds_read_b128 v[174:177], v168 offset:51200
	ds_read_b128 v[188:191], v168 offset:52224
	s_add_u32 s0, s82, 0x80000
	s_addc_u32 s1, s83, 0
	s_mov_b32 m0, s89
	ds_read_b128 v[198:201], v196 offset:32768
	ds_read_b128 v[202:205], v196 offset:33792
	ds_read_b128 v[206:209], v196 offset:34816
	ds_read_b128 v[210:213], v196 offset:35840
	ds_read_b128 v[214:217], v196 offset:36864
	ds_read_b128 v[218:221], v196 offset:37888
	ds_read_b128 v[222:225], v196 offset:38912
	ds_read_b128 v[226:229], v196 offset:39936
	global_load_lds_dwordx4 v130, s[0:1]
	s_mov_b32 m0, s90
	s_nop 0
	global_load_lds_dwordx4 v132, s[0:1]
	s_waitcnt vmcnt(8)
	s_waitcnt lgkmcnt(0)
	s_setprio 1
	s_barrier
	v_mfma_f32_16x16x32_bf16 v[126:129], v[142:145], v[198:201], v[126:129]
	v_mfma_f32_16x16x32_bf16 v[126:129], v[146:149], v[202:205], v[126:129]
	v_mfma_f32_16x16x32_bf16 v[122:125], v[142:145], v[206:209], v[122:125]
	v_mfma_f32_16x16x32_bf16 v[122:125], v[146:149], v[210:213], v[122:125]
	v_mfma_f32_16x16x32_bf16 v[118:121], v[142:145], v[214:217], v[118:121]
	v_mfma_f32_16x16x32_bf16 v[118:121], v[146:149], v[218:221], v[118:121]
	v_mfma_f32_16x16x32_bf16 v[114:117], v[142:145], v[222:225], v[114:117]
	v_mfma_f32_16x16x32_bf16 v[114:117], v[146:149], v[226:229], v[114:117]
	v_mfma_f32_16x16x32_bf16 v[98:101], v[150:153], v[222:225], v[98:101]
	v_mfma_f32_16x16x32_bf16 v[98:101], v[154:157], v[226:229], v[98:101]
	v_mfma_f32_16x16x32_bf16 v[102:105], v[150:153], v[214:217], v[102:105]
	v_mfma_f32_16x16x32_bf16 v[102:105], v[154:157], v[218:221], v[102:105]
	v_mfma_f32_16x16x32_bf16 v[106:109], v[150:153], v[206:209], v[106:109]
	v_mfma_f32_16x16x32_bf16 v[106:109], v[154:157], v[210:213], v[106:109]
	v_mfma_f32_16x16x32_bf16 v[110:113], v[150:153], v[198:201], v[110:113]
	v_mfma_f32_16x16x32_bf16 v[110:113], v[154:157], v[202:205], v[110:113]
	v_mfma_f32_16x16x32_bf16 v[82:85], v[158:161], v[198:201], v[82:85]
	v_mfma_f32_16x16x32_bf16 v[82:85], v[162:165], v[202:205], v[82:85]
	v_mfma_f32_16x16x32_bf16 v[70:73], v[158:161], v[206:209], v[70:73]
	v_mfma_f32_16x16x32_bf16 v[70:73], v[162:165], v[210:213], v[70:73]
	v_mfma_f32_16x16x32_bf16 v[66:69], v[158:161], v[214:217], v[66:69]
	v_mfma_f32_16x16x32_bf16 v[66:69], v[162:165], v[218:221], v[66:69]
	v_mfma_f32_16x16x32_bf16 v[58:61], v[158:161], v[222:225], v[58:61]
	v_mfma_f32_16x16x32_bf16 v[58:61], v[162:165], v[226:229], v[58:61]
	v_mfma_f32_16x16x32_bf16 v[18:21], v[174:177], v[222:225], v[18:21]
	v_mfma_f32_16x16x32_bf16 v[18:21], v[188:191], v[226:229], v[18:21]
	v_mfma_f32_16x16x32_bf16 v[22:25], v[174:177], v[214:217], v[22:25]
	v_mfma_f32_16x16x32_bf16 v[22:25], v[188:191], v[218:221], v[22:25]
	v_mfma_f32_16x16x32_bf16 v[26:29], v[174:177], v[206:209], v[26:29]
	v_mfma_f32_16x16x32_bf16 v[26:29], v[188:191], v[210:213], v[26:29]
	v_mfma_f32_16x16x32_bf16 v[30:33], v[174:177], v[198:201], v[30:33]
	v_mfma_f32_16x16x32_bf16 v[30:33], v[188:191], v[202:205], v[30:33]
	s_barrier
	s_setprio 0
	s_add_i32 s0, s40, s87
	s_mov_b32 m0, s0
	ds_read_b128 v[198:201], v196 offset:49152
	ds_read_b128 v[202:205], v196 offset:50176
	ds_read_b128 v[206:209], v196 offset:51200
	ds_read_b128 v[210:213], v196 offset:52224
	ds_read_b128 v[214:217], v196 offset:53248
	ds_read_b128 v[218:221], v196 offset:54272
	ds_read_b128 v[222:225], v196 offset:55296
	ds_read_b128 v[226:229], v196 offset:56320
	s_add_u32 s100, s80, 0x80
	s_addc_u32 s101, s81, 0
	global_load_lds_dwordx4 v182, s[100:101]
	s_add_i32 m0, s0, 0x2000
	s_add_u32 s0, s80, 0x80080
	s_addc_u32 s1, s81, 0
	s_add_i32 s40, s41, s87
	global_load_lds_dwordx4 v134, s[100:101]
	s_mov_b32 m0, s40
	s_nop 0
	global_load_lds_dwordx4 v182, s[0:1]
	s_add_i32 m0, s40, 0x2000
	s_nop 0
	global_load_lds_dwordx4 v134, s[0:1]
	s_mov_b32 m0, s94
	s_nop 0
	s_add_u32 s100, s82, 0x80
	s_addc_u32 s101, s83, 0
	global_load_lds_dwordx4 v130, s[100:101]
	s_mov_b32 m0, s95
	s_nop 0
	global_load_lds_dwordx4 v132, s[100:101]
	s_waitcnt vmcnt(8)
	s_waitcnt lgkmcnt(0)
	s_setprio 1
	s_barrier
	v_mfma_f32_16x16x32_bf16 v[94:97], v[142:145], v[198:201], v[94:97]
	v_mfma_f32_16x16x32_bf16 v[94:97], v[146:149], v[202:205], v[94:97]
	v_mfma_f32_16x16x32_bf16 v[90:93], v[142:145], v[206:209], v[90:93]
	v_mfma_f32_16x16x32_bf16 v[90:93], v[146:149], v[210:213], v[90:93]
	v_mfma_f32_16x16x32_bf16 v[86:89], v[142:145], v[214:217], v[86:89]
	v_mfma_f32_16x16x32_bf16 v[86:89], v[146:149], v[218:221], v[86:89]
	v_mfma_f32_16x16x32_bf16 v[78:81], v[142:145], v[222:225], v[78:81]
	v_mfma_f32_16x16x32_bf16 v[78:81], v[146:149], v[226:229], v[78:81]
	v_mfma_f32_16x16x32_bf16 v[50:53], v[150:153], v[222:225], v[50:53]
	v_mfma_f32_16x16x32_bf16 v[50:53], v[154:157], v[226:229], v[50:53]
	v_mfma_f32_16x16x32_bf16 v[54:57], v[150:153], v[214:217], v[54:57]
	v_mfma_f32_16x16x32_bf16 v[54:57], v[154:157], v[218:221], v[54:57]
	v_mfma_f32_16x16x32_bf16 v[62:65], v[150:153], v[206:209], v[62:65]
	v_mfma_f32_16x16x32_bf16 v[62:65], v[154:157], v[210:213], v[62:65]
	v_mfma_f32_16x16x32_bf16 v[74:77], v[150:153], v[198:201], v[74:77]
	v_mfma_f32_16x16x32_bf16 v[74:77], v[154:157], v[202:205], v[74:77]
	v_mfma_f32_16x16x32_bf16 v[46:49], v[158:161], v[198:201], v[46:49]
	v_mfma_f32_16x16x32_bf16 v[46:49], v[162:165], v[202:205], v[46:49]
	v_mfma_f32_16x16x32_bf16 v[42:45], v[158:161], v[206:209], v[42:45]
	v_mfma_f32_16x16x32_bf16 v[42:45], v[162:165], v[210:213], v[42:45]
	v_mfma_f32_16x16x32_bf16 v[38:41], v[158:161], v[214:217], v[38:41]
	v_mfma_f32_16x16x32_bf16 v[38:41], v[162:165], v[218:221], v[38:41]
	v_mfma_f32_16x16x32_bf16 v[34:37], v[158:161], v[222:225], v[34:37]
	v_mfma_f32_16x16x32_bf16 v[34:37], v[162:165], v[226:229], v[34:37]
	v_mfma_f32_16x16x32_bf16 v[2:5], v[174:177], v[222:225], v[2:5]
	v_mfma_f32_16x16x32_bf16 v[2:5], v[188:191], v[226:229], v[2:5]
	v_mfma_f32_16x16x32_bf16 v[6:9], v[174:177], v[214:217], v[6:9]
	v_mfma_f32_16x16x32_bf16 v[6:9], v[188:191], v[218:221], v[6:9]
	v_mfma_f32_16x16x32_bf16 v[10:13], v[174:177], v[206:209], v[10:13]
	v_mfma_f32_16x16x32_bf16 v[10:13], v[188:191], v[210:213], v[10:13]
	v_mfma_f32_16x16x32_bf16 v[14:17], v[174:177], v[198:201], v[14:17]
	v_mfma_f32_16x16x32_bf16 v[14:17], v[188:191], v[202:205], v[14:17]
	s_barrier
	s_setprio 0
	s_add_i32 s37, s37, 2
	s_add_u32 s78, s78, 0x100
	s_addc_u32 s79, s79, 0
	s_add_u32 s33, s33, 0x100
	s_addc_u32 s35, s35, 0
	s_cmp_gt_u32 s37, 29
	s_cbranch_scc0 .LBB0_234
	s_and_b64 vcc, exec, s[64:65]
	s_cbranch_vccz .LBB0_237
	s_barrier

; #define PG8_STAGE(bufoff, gbase, voff) do { _Pragma("unroll") for (int _i = 0; _i < 2; ++_i) \
;         __builtin_amdgcn_global_load_lds((const unsigned*)((const char*)(gbase) + (voff)[_i]), (PG8_LAS unsigned*)(lds + (bufoff) + ldsw + _i * 8192), 16, 0, 0); } while (0)
; #define PG8_LDA(dst, b, h) do { _Pragma("unroll") for (int m = 0; m < 4; ++m) _Pragma("unroll") for (int k = 0; k < 2; ++k) dst[m][k] = *(const PG8_LAS bf16x8*)(lds + PG8_SA(b, h) + aoff + m * 2048 + k * 1024); } while (0)
; #define PG8_LDB(dst, b, h) do { _Pragma("unroll") for (int n = 0; n < 2; ++n) _Pragma("unroll") for (int k = 0; k < 2; ++k) dst[n][k] = *(const PG8_LAS bf16x8*)(lds + PG8_SB(b, h) + boff + n * 2048 + k * 1024); } while (0)
; #define PG8_WAIT_L(n) asm volatile("s_waitcnt lgkmcnt(" #n ")" ::: "memory")
; #define PG8_WAIT_V_SEL(sel) asm volatile("s_cmp_eq_u32 %0, 0\n\ts_cbranch_scc1 .Lw8_%=\n\ts_waitcnt vmcnt(22)\n\ts_branch .Lwd_%=\n.Lw8_%=:\n\ts_waitcnt vmcnt(8)\n.Lwd_%=:" :: "s"(sel) : "memory", "scc")
; #define PG8_BAR __builtin_amdgcn_s_barrier()
; #define PG8_SCHED __builtin_amdgcn_sched_barrier(0)
;     ...
;         for (int t = 0; t < nt * KREP; t += 2) {
;             const bool last = (t == nt * KREP - 2);
;             const int t1w = KREP > 1 ? ((t + 1) & (nt - 1)) : t + 1, t2w = KREP > 1 ? ((t + 2) & (nt - 1)) : t + 2;
;             const char* a1 = cA + (size_t)t1w * kstep;
;             const char* a2 = last ? nA : cA + (size_t)t2w * kstep; const char* b2 = last ? nB : cB + (size_t)t2w * kstep;
;             const char* a3 = a2 + kstep; const char* b3 = b2 + kstep;
;             if (last && has_next) S.a_ready(nxt);
;             const int relax = __builtin_amdgcn_readfirstlane((MK_RELAXW && t == 0 && ui > 0) ? 1 : 0);
;             if constexpr (SP2) {
;             PG8_LDB(B0, 0, 0); PG8_LDB(B1, 0, 1); PG8_SCHED; PG8_LDA(At, 0, 0); PG8_STAGE(PG8_SA(1, 1), a1 + hstep, voffA);
;             PG8_WAIT_V_SEL(relax);
;             PG8_WAIT_L(0); PG8_BAR; PG8_MMA(0, 0, At, B0); PG8_MMA(0, 1, At, B1); PG8_BAR; PG8_SCHED;
;             PG8_LDA(At, 0, 1); PG8_STAGE(PG8_SB(0, 0), b2, voffB); PG8_STAGE(PG8_SB(0, 1), b2 + hstep, voffB); PG8_STAGE(PG8_SA(0, 0), a2, voffA);
;             PG8_WAIT_V_SEL(relax);
;             PG8_WAIT_L(0); PG8_BAR; PG8_MMA(1, 0, At, B0); PG8_MMA(1, 1, At, B1); PG8_BAR; PG8_SCHED;
.LBB0_541:
	s_add_u32 s0, s82, 0xfff80080
	s_addc_u32 s1, s83, -1
	s_add_i32 s79, 0, 0x10000
	s_cmp_eq_u32 s73, 28
	s_cselect_b32 s87, s40, s1
	s_cselect_b32 s86, s41, s0
	s_cselect_b32 s85, s57, s71
	s_cselect_b32 s84, s58, s59
	s_add_i32 s81, 0, 0x14000
	ds_read_b128 v[90:93], v210
	ds_read_b128 v[94:97], v210 offset:1024
	ds_read_b128 v[98:101], v210 offset:2048
	ds_read_b128 v[102:105], v210 offset:3072
	ds_read_b128 v[146:149], v210 offset:16384
	ds_read_b128 v[150:153], v210 offset:17408
	ds_read_b128 v[154:157], v210 offset:18432
	ds_read_b128 v[158:161], v210 offset:19456
	s_add_i32 m0, s44, 0xc000
	ds_read_b128 v[162:165], v230
	ds_read_b128 v[166:169], v230 offset:1024
	ds_read_b128 v[184:187], v230 offset:2048
	ds_read_b128 v[190:193], v230 offset:3072
	ds_read_b128 v[194:197], v230 offset:4096
	ds_read_b128 v[198:201], v230 offset:5120
	ds_read_b128 v[202:205], v230 offset:6144
	ds_read_b128 v[206:209], v230 offset:7168
	global_load_lds_dwordx4 v180, s[82:83]
	s_add_i32 m0, s44, 0xe000
	s_nop 0
	global_load_lds_dwordx4 v188, s[82:83]
	s_waitcnt vmcnt(8)
	s_waitcnt lgkmcnt(0)
	s_setprio 1
	s_barrier
	v_mfma_f32_16x16x32_bf16 v[142:145], v[90:93], v[162:165], v[142:145]
	v_mfma_f32_16x16x32_bf16 v[142:145], v[94:97], v[166:169], v[142:145]
	v_mfma_f32_16x16x32_bf16 v[126:129], v[90:93], v[184:187], v[126:129]
	v_mfma_f32_16x16x32_bf16 v[126:129], v[94:97], v[190:193], v[126:129]
	v_mfma_f32_16x16x32_bf16 v[110:113], v[90:93], v[194:197], v[110:113]
	v_mfma_f32_16x16x32_bf16 v[110:113], v[94:97], v[198:201], v[110:113]
	v_mfma_f32_16x16x32_bf16 v[78:81], v[90:93], v[202:205], v[78:81]
	v_mfma_f32_16x16x32_bf16 v[78:81], v[94:97], v[206:209], v[78:81]
	v_mfma_f32_16x16x32_bf16 v[74:77], v[98:101], v[202:205], v[74:77]
	v_mfma_f32_16x16x32_bf16 v[74:77], v[102:105], v[206:209], v[74:77]
	v_mfma_f32_16x16x32_bf16 v[106:109], v[98:101], v[194:197], v[106:109]
	v_mfma_f32_16x16x32_bf16 v[106:109], v[102:105], v[198:201], v[106:109]
	v_mfma_f32_16x16x32_bf16 v[122:125], v[98:101], v[184:187], v[122:125]
	v_mfma_f32_16x16x32_bf16 v[122:125], v[102:105], v[190:193], v[122:125]
	v_mfma_f32_16x16x32_bf16 v[138:141], v[98:101], v[162:165], v[138:141]
	v_mfma_f32_16x16x32_bf16 v[138:141], v[102:105], v[166:169], v[138:141]
	v_mfma_f32_16x16x32_bf16 v[134:137], v[146:149], v[162:165], v[134:137]
	v_mfma_f32_16x16x32_bf16 v[134:137], v[150:153], v[166:169], v[134:137]
	v_mfma_f32_16x16x32_bf16 v[118:121], v[146:149], v[184:187], v[118:121]
	v_mfma_f32_16x16x32_bf16 v[118:121], v[150:153], v[190:193], v[118:121]
	v_mfma_f32_16x16x32_bf16 v[86:89], v[146:149], v[194:197], v[86:89]
	v_mfma_f32_16x16x32_bf16 v[86:89], v[150:153], v[198:201], v[86:89]
	v_mfma_f32_16x16x32_bf16 v[70:73], v[146:149], v[202:205], v[70:73]
	v_mfma_f32_16x16x32_bf16 v[70:73], v[150:153], v[206:209], v[70:73]
	v_mfma_f32_16x16x32_bf16 v[66:69], v[154:157], v[202:205], v[66:69]
	v_mfma_f32_16x16x32_bf16 v[66:69], v[158:161], v[206:209], v[66:69]
	v_mfma_f32_16x16x32_bf16 v[82:85], v[154:157], v[194:197], v[82:85]
	v_mfma_f32_16x16x32_bf16 v[82:85], v[158:161], v[198:201], v[82:85]
	v_mfma_f32_16x16x32_bf16 v[114:117], v[154:157], v[184:187], v[114:117]
	v_mfma_f32_16x16x32_bf16 v[114:117], v[158:161], v[190:193], v[114:117]
	v_mfma_f32_16x16x32_bf16 v[130:133], v[154:157], v[162:165], v[130:133]
	v_mfma_f32_16x16x32_bf16 v[130:133], v[158:161], v[166:169], v[130:133]
	s_barrier
	s_setprio 0
	s_add_i32 s0, s79, s30
	s_mov_b32 m0, s0
	ds_read_b128 v[162:165], v230 offset:16384
	ds_read_b128 v[166:169], v230 offset:17408
	ds_read_b128 v[184:187], v230 offset:18432
	ds_read_b128 v[190:193], v230 offset:19456
	ds_read_b128 v[194:197], v230 offset:20480
	ds_read_b128 v[198:201], v230 offset:21504
	ds_read_b128 v[202:205], v230 offset:22528
	ds_read_b128 v[206:209], v230 offset:23552
	global_load_lds_dwordx4 v182, s[84:85]
	s_add_i32 m0, s0, 0x2000
	s_add_u32 s0, s84, 0x80000
	s_addc_u32 s1, s85, 0
	s_add_i32 s79, s81, s30
	global_load_lds_dwordx4 v178, s[84:85]
	s_mov_b32 m0, s79
	s_nop 0
	global_load_lds_dwordx4 v182, s[0:1]
	s_add_i32 m0, s79, 0x2000
	s_nop 0
	global_load_lds_dwordx4 v178, s[0:1]
	s_mov_b32 m0, s44
	s_nop 0
	global_load_lds_dwordx4 v174, s[86:87]
	s_mov_b32 m0, s45
	s_nop 0
	global_load_lds_dwordx4 v176, s[86:87]
	s_waitcnt vmcnt(8)
	s_waitcnt lgkmcnt(0)
	s_setprio 1
	s_barrier
	v_mfma_f32_16x16x32_bf16 v[62:65], v[90:93], v[162:165], v[62:65]
	v_mfma_f32_16x16x32_bf16 v[62:65], v[94:97], v[166:169], v[62:65]
	v_mfma_f32_16x16x32_bf16 v[46:49], v[90:93], v[184:187], v[46:49]
	v_mfma_f32_16x16x32_bf16 v[46:49], v[94:97], v[190:193], v[46:49]
	v_mfma_f32_16x16x32_bf16 v[30:33], v[90:93], v[194:197], v[30:33]
	v_mfma_f32_16x16x32_bf16 v[30:33], v[94:97], v[198:201], v[30:33]
	v_mfma_f32_16x16x32_bf16 v[14:17], v[90:93], v[202:205], v[14:17]
	v_mfma_f32_16x16x32_bf16 v[14:17], v[94:97], v[206:209], v[14:17]
	v_mfma_f32_16x16x32_bf16 v[10:13], v[98:101], v[202:205], v[10:13]
	v_mfma_f32_16x16x32_bf16 v[10:13], v[102:105], v[206:209], v[10:13]
	v_mfma_f32_16x16x32_bf16 v[26:29], v[98:101], v[194:197], v[26:29]
	v_mfma_f32_16x16x32_bf16 v[26:29], v[102:105], v[198:201], v[26:29]
	v_mfma_f32_16x16x32_bf16 v[42:45], v[98:101], v[184:187], v[42:45]
	v_mfma_f32_16x16x32_bf16 v[42:45], v[102:105], v[190:193], v[42:45]
	v_mfma_f32_16x16x32_bf16 v[58:61], v[98:101], v[162:165], v[58:61]
	v_mfma_f32_16x16x32_bf16 v[58:61], v[102:105], v[166:169], v[58:61]
	v_mfma_f32_16x16x32_bf16 v[54:57], v[146:149], v[162:165], v[54:57]
	v_mfma_f32_16x16x32_bf16 v[54:57], v[150:153], v[166:169], v[54:57]
	v_mfma_f32_16x16x32_bf16 v[38:41], v[146:149], v[184:187], v[38:41]
	v_mfma_f32_16x16x32_bf16 v[38:41], v[150:153], v[190:193], v[38:41]
	v_mfma_f32_16x16x32_bf16 v[22:25], v[146:149], v[194:197], v[22:25]
	v_mfma_f32_16x16x32_bf16 v[22:25], v[150:153], v[198:201], v[22:25]
	v_mfma_f32_16x16x32_bf16 v[6:9], v[146:149], v[202:205], v[6:9]
	v_mfma_f32_16x16x32_bf16 v[6:9], v[150:153], v[206:209], v[6:9]
	v_mfma_f32_16x16x32_bf16 v[2:5], v[154:157], v[202:205], v[2:5]
	v_mfma_f32_16x16x32_bf16 v[2:5], v[158:161], v[206:209], v[2:5]
	v_mfma_f32_16x16x32_bf16 v[18:21], v[154:157], v[194:197], v[18:21]
	v_mfma_f32_16x16x32_bf16 v[18:21], v[158:161], v[198:201], v[18:21]
	v_mfma_f32_16x16x32_bf16 v[34:37], v[154:157], v[184:187], v[34:37]
	v_mfma_f32_16x16x32_bf16 v[34:37], v[158:161], v[190:193], v[34:37]
	v_mfma_f32_16x16x32_bf16 v[50:53], v[154:157], v[162:165], v[50:53]
	v_mfma_f32_16x16x32_bf16 v[50:53], v[158:161], v[166:169], v[50:53]
	s_barrier
; #define PG8_STAGE(bufoff, gbase, voff) do { _Pragma("unroll") for (int _i = 0; _i < 2; ++_i) \
;         __builtin_amdgcn_global_load_lds((const unsigned*)((const char*)(gbase) + (voff)[_i]), (PG8_LAS unsigned*)(lds + (bufoff) + ldsw + _i * 8192), 16, 0, 0); } while (0)
; #define PG8_LDA(dst, b, h) do { _Pragma("unroll") for (int m = 0; m < 4; ++m) _Pragma("unroll") for (int k = 0; k < 2; ++k) dst[m][k] = *(const PG8_LAS bf16x8*)(lds + PG8_SA(b, h) + aoff + m * 2048 + k * 1024); } while (0)
; #define PG8_LDB(dst, b, h) do { _Pragma("unroll") for (int n = 0; n < 2; ++n) _Pragma("unroll") for (int k = 0; k < 2; ++k) dst[n][k] = *(const PG8_LAS bf16x8*)(lds + PG8_SB(b, h) + boff + n * 2048 + k * 1024); } while (0)
; #define PG8_WAIT_V(n) asm volatile("s_waitcnt vmcnt(" #n ")" ::: "memory")
; #define PG8_WAIT_L(n) asm volatile("s_waitcnt lgkmcnt(" #n ")" ::: "memory")
; #define PG8_BAR __builtin_amdgcn_s_barrier()
; #define PG8_SCHED __builtin_amdgcn_sched_barrier(0)
;     ...
;             PG8_LDB(B0, 1, 0); PG8_LDB(B1, 1, 1); PG8_SCHED; PG8_LDA(At, 1, 0); PG8_STAGE(PG8_SA(0, 1), a2 + hstep, voffA);
;             PG8_WAIT_V(8); PG8_WAIT_L(0); PG8_BAR; PG8_MMA(0, 0, At, B0); PG8_MMA(0, 1, At, B1); PG8_BAR; PG8_SCHED;
;             PG8_LDA(At, 1, 1); PG8_STAGE(PG8_SB(1, 0), b3, voffB); PG8_STAGE(PG8_SB(1, 1), b3 + hstep, voffB); PG8_STAGE(PG8_SA(1, 0), a3, voffA);
;             PG8_WAIT_V(8); PG8_WAIT_L(0); PG8_BAR; PG8_MMA(1, 0, At, B0); PG8_MMA(1, 1, At, B1); PG8_BAR; PG8_SCHED;
;     ...
;         if constexpr (ALIGN_EPI) { if (wr == 0) PG8_BAR; }
	s_setprio 0
	s_add_i32 s79, 0, 0x18000
	s_add_i32 s81, 0, 0x1c000
	ds_read_b128 v[90:93], v210 offset:32768
	ds_read_b128 v[94:97], v210 offset:33792
	ds_read_b128 v[98:101], v210 offset:34816
	ds_read_b128 v[102:105], v210 offset:35840
	ds_read_b128 v[146:149], v210 offset:49152
	ds_read_b128 v[150:153], v210 offset:50176
	ds_read_b128 v[154:157], v210 offset:51200
	ds_read_b128 v[158:161], v210 offset:52224
	s_add_u32 s0, s86, 0x80000
	s_addc_u32 s1, s87, 0
	s_mov_b32 m0, s46
	ds_read_b128 v[162:165], v230 offset:32768
	ds_read_b128 v[166:169], v230 offset:33792
	ds_read_b128 v[184:187], v230 offset:34816
	ds_read_b128 v[190:193], v230 offset:35840
	ds_read_b128 v[194:197], v230 offset:36864
	ds_read_b128 v[198:201], v230 offset:37888
	ds_read_b128 v[202:205], v230 offset:38912
	ds_read_b128 v[206:209], v230 offset:39936
	global_load_lds_dwordx4 v174, s[0:1]
	s_mov_b32 m0, s47
	s_nop 0
	global_load_lds_dwordx4 v176, s[0:1]
	s_waitcnt vmcnt(8)
	s_waitcnt lgkmcnt(0)
	s_setprio 1
	s_barrier
	v_mfma_f32_16x16x32_bf16 v[142:145], v[90:93], v[162:165], v[142:145]
	v_mfma_f32_16x16x32_bf16 v[142:145], v[94:97], v[166:169], v[142:145]
	v_mfma_f32_16x16x32_bf16 v[126:129], v[90:93], v[184:187], v[126:129]
	v_mfma_f32_16x16x32_bf16 v[126:129], v[94:97], v[190:193], v[126:129]
	v_mfma_f32_16x16x32_bf16 v[110:113], v[90:93], v[194:197], v[110:113]
	v_mfma_f32_16x16x32_bf16 v[110:113], v[94:97], v[198:201], v[110:113]
	v_mfma_f32_16x16x32_bf16 v[78:81], v[90:93], v[202:205], v[78:81]
	v_mfma_f32_16x16x32_bf16 v[78:81], v[94:97], v[206:209], v[78:81]
	v_mfma_f32_16x16x32_bf16 v[74:77], v[98:101], v[202:205], v[74:77]
	v_mfma_f32_16x16x32_bf16 v[74:77], v[102:105], v[206:209], v[74:77]
	v_mfma_f32_16x16x32_bf16 v[106:109], v[98:101], v[194:197], v[106:109]
	v_mfma_f32_16x16x32_bf16 v[106:109], v[102:105], v[198:201], v[106:109]
	v_mfma_f32_16x16x32_bf16 v[122:125], v[98:101], v[184:187], v[122:125]
	v_mfma_f32_16x16x32_bf16 v[122:125], v[102:105], v[190:193], v[122:125]
	v_mfma_f32_16x16x32_bf16 v[138:141], v[98:101], v[162:165], v[138:141]
	v_mfma_f32_16x16x32_bf16 v[138:141], v[102:105], v[166:169], v[138:141]
	v_mfma_f32_16x16x32_bf16 v[134:137], v[146:149], v[162:165], v[134:137]
	v_mfma_f32_16x16x32_bf16 v[134:137], v[150:153], v[166:169], v[134:137]
	v_mfma_f32_16x16x32_bf16 v[118:121], v[146:149], v[184:187], v[118:121]
	v_mfma_f32_16x16x32_bf16 v[118:121], v[150:153], v[190:193], v[118:121]
	v_mfma_f32_16x16x32_bf16 v[86:89], v[146:149], v[194:197], v[86:89]
	v_mfma_f32_16x16x32_bf16 v[86:89], v[150:153], v[198:201], v[86:89]
	v_mfma_f32_16x16x32_bf16 v[70:73], v[146:149], v[202:205], v[70:73]
	v_mfma_f32_16x16x32_bf16 v[70:73], v[150:153], v[206:209], v[70:73]
	v_mfma_f32_16x16x32_bf16 v[66:69], v[154:157], v[202:205], v[66:69]
	v_mfma_f32_16x16x32_bf16 v[66:69], v[158:161], v[206:209], v[66:69]
	v_mfma_f32_16x16x32_bf16 v[82:85], v[154:157], v[194:197], v[82:85]
	v_mfma_f32_16x16x32_bf16 v[82:85], v[158:161], v[198:201], v[82:85]
	v_mfma_f32_16x16x32_bf16 v[114:117], v[154:157], v[184:187], v[114:117]
	v_mfma_f32_16x16x32_bf16 v[114:117], v[158:161], v[190:193], v[114:117]
	v_mfma_f32_16x16x32_bf16 v[130:133], v[154:157], v[162:165], v[130:133]
	v_mfma_f32_16x16x32_bf16 v[130:133], v[158:161], v[166:169], v[130:133]
	s_barrier
	s_setprio 0
	s_add_i32 s0, s79, s30
	s_mov_b32 m0, s0
	ds_read_b128 v[162:165], v230 offset:49152
	ds_read_b128 v[166:169], v230 offset:50176
	ds_read_b128 v[184:187], v230 offset:51200
	ds_read_b128 v[190:193], v230 offset:52224
	ds_read_b128 v[194:197], v230 offset:53248
	ds_read_b128 v[198:201], v230 offset:54272
	ds_read_b128 v[202:205], v230 offset:55296
	ds_read_b128 v[206:209], v230 offset:56320
	s_add_u32 s100, s84, 0x80
	s_addc_u32 s101, s85, 0
	global_load_lds_dwordx4 v182, s[100:101]
	s_add_i32 m0, s0, 0x2000
	s_add_u32 s0, s84, 0x80080
	s_addc_u32 s1, s85, 0
	s_add_i32 s79, s81, s30
	global_load_lds_dwordx4 v178, s[100:101]
	s_mov_b32 m0, s79
	s_nop 0
	global_load_lds_dwordx4 v182, s[0:1]
	s_add_i32 m0, s79, 0x2000
	s_nop 0
	global_load_lds_dwordx4 v178, s[0:1]
	s_mov_b32 m0, s49
	s_nop 0
	s_add_u32 s100, s86, 0x80
	s_addc_u32 s101, s87, 0
	global_load_lds_dwordx4 v174, s[100:101]
	s_mov_b32 m0, s50
	s_nop 0
	global_load_lds_dwordx4 v176, s[100:101]
	s_waitcnt vmcnt(8)
	s_waitcnt lgkmcnt(0)
	s_setprio 1
	s_barrier
	v_mfma_f32_16x16x32_bf16 v[62:65], v[90:93], v[162:165], v[62:65]
	v_mfma_f32_16x16x32_bf16 v[62:65], v[94:97], v[166:169], v[62:65]
	v_mfma_f32_16x16x32_bf16 v[46:49], v[90:93], v[184:187], v[46:49]
	v_mfma_f32_16x16x32_bf16 v[46:49], v[94:97], v[190:193], v[46:49]
	v_mfma_f32_16x16x32_bf16 v[30:33], v[90:93], v[194:197], v[30:33]
	v_mfma_f32_16x16x32_bf16 v[30:33], v[94:97], v[198:201], v[30:33]
	v_mfma_f32_16x16x32_bf16 v[14:17], v[90:93], v[202:205], v[14:17]
	v_mfma_f32_16x16x32_bf16 v[14:17], v[94:97], v[206:209], v[14:17]
	v_mfma_f32_16x16x32_bf16 v[10:13], v[98:101], v[202:205], v[10:13]
	v_mfma_f32_16x16x32_bf16 v[10:13], v[102:105], v[206:209], v[10:13]
	v_mfma_f32_16x16x32_bf16 v[26:29], v[98:101], v[194:197], v[26:29]
	v_mfma_f32_16x16x32_bf16 v[26:29], v[102:105], v[198:201], v[26:29]
	v_mfma_f32_16x16x32_bf16 v[42:45], v[98:101], v[184:187], v[42:45]
	v_mfma_f32_16x16x32_bf16 v[42:45], v[102:105], v[190:193], v[42:45]
	v_mfma_f32_16x16x32_bf16 v[58:61], v[98:101], v[162:165], v[58:61]
	v_mfma_f32_16x16x32_bf16 v[58:61], v[102:105], v[166:169], v[58:61]
	v_mfma_f32_16x16x32_bf16 v[54:57], v[146:149], v[162:165], v[54:57]
	v_mfma_f32_16x16x32_bf16 v[54:57], v[150:153], v[166:169], v[54:57]
	v_mfma_f32_16x16x32_bf16 v[38:41], v[146:149], v[184:187], v[38:41]
	v_mfma_f32_16x16x32_bf16 v[38:41], v[150:153], v[190:193], v[38:41]
	v_mfma_f32_16x16x32_bf16 v[22:25], v[146:149], v[194:197], v[22:25]
	v_mfma_f32_16x16x32_bf16 v[22:25], v[150:153], v[198:201], v[22:25]
	v_mfma_f32_16x16x32_bf16 v[6:9], v[146:149], v[202:205], v[6:9]
	v_mfma_f32_16x16x32_bf16 v[6:9], v[150:153], v[206:209], v[6:9]
	v_mfma_f32_16x16x32_bf16 v[2:5], v[154:157], v[202:205], v[2:5]
	v_mfma_f32_16x16x32_bf16 v[2:5], v[158:161], v[206:209], v[2:5]
	v_mfma_f32_16x16x32_bf16 v[18:21], v[154:157], v[194:197], v[18:21]
	v_mfma_f32_16x16x32_bf16 v[18:21], v[158:161], v[198:201], v[18:21]
	v_mfma_f32_16x16x32_bf16 v[34:37], v[154:157], v[184:187], v[34:37]
	v_mfma_f32_16x16x32_bf16 v[34:37], v[158:161], v[190:193], v[34:37]
	v_mfma_f32_16x16x32_bf16 v[50:53], v[154:157], v[162:165], v[50:53]
	v_mfma_f32_16x16x32_bf16 v[50:53], v[158:161], v[166:169], v[50:53]
	s_barrier
	s_setprio 0
	s_add_i32 s73, s73, 2
	s_add_u32 s82, s82, 0x100
	s_addc_u32 s83, s83, 0
	s_add_u32 s59, s59, 0x100
	s_addc_u32 s71, s71, 0
	s_cmp_gt_u32 s73, 29
	s_cbranch_scc0 .LBB0_541
	s_and_b64 vcc, exec, s[68:69]
	s_cbranch_vccz .LBB0_544
	s_barrier

; #define PG8_STAGE(bufoff, gbase, voff) do { _Pragma("unroll") for (int _i = 0; _i < 2; ++_i) \
;         __builtin_amdgcn_global_load_lds((const unsigned*)((const char*)(gbase) + (voff)[_i]), (PG8_LAS unsigned*)(lds + (bufoff) + ldsw + _i * 8192), 16, 0, 0); } while (0)
; #define PG8_LDA(dst, b, h) do { _Pragma("unroll") for (int m = 0; m < 4; ++m) _Pragma("unroll") for (int k = 0; k < 2; ++k) dst[m][k] = *(const PG8_LAS bf16x8*)(lds + PG8_SA(b, h) + aoff + m * 2048 + k * 1024); } while (0)
; #define PG8_LDB(dst, b, h) do { _Pragma("unroll") for (int n = 0; n < 2; ++n) _Pragma("unroll") for (int k = 0; k < 2; ++k) dst[n][k] = *(const PG8_LAS bf16x8*)(lds + PG8_SB(b, h) + boff + n * 2048 + k * 1024); } while (0)
; #define PG8_WAIT_L(n) asm volatile("s_waitcnt lgkmcnt(" #n ")" ::: "memory")
; #define PG8_WAIT_V_SEL(sel) asm volatile("s_cmp_eq_u32 %0, 0\n\ts_cbranch_scc1 .Lw8_%=\n\ts_waitcnt vmcnt(22)\n\ts_branch .Lwd_%=\n.Lw8_%=:\n\ts_waitcnt vmcnt(8)\n.Lwd_%=:" :: "s"(sel) : "memory", "scc")
; #define PG8_BAR __builtin_amdgcn_s_barrier()
; #define PG8_SCHED __builtin_amdgcn_sched_barrier(0)
;     ...
;         for (int t = 0; t < nt * KREP; t += 2) {
;             const bool last = (t == nt * KREP - 2);
;             const int t1w = KREP > 1 ? ((t + 1) & (nt - 1)) : t + 1, t2w = KREP > 1 ? ((t + 2) & (nt - 1)) : t + 2;
;             const char* a1 = cA + (size_t)t1w * kstep;
;             const char* a2 = last ? nA : cA + (size_t)t2w * kstep; const char* b2 = last ? nB : cB + (size_t)t2w * kstep;
;             const char* a3 = a2 + kstep; const char* b3 = b2 + kstep;
;             if (last && has_next) S.a_ready(nxt);
;             const int relax = __builtin_amdgcn_readfirstlane((MK_RELAXW && t == 0 && ui > 0) ? 1 : 0);
;             if constexpr (SP2) {
;             PG8_LDB(B0, 0, 0); PG8_LDB(B1, 0, 1); PG8_SCHED; PG8_LDA(At, 0, 0); PG8_STAGE(PG8_SA(1, 1), a1 + hstep, voffA);
;             PG8_WAIT_V_SEL(relax);
;             PG8_WAIT_L(0); PG8_BAR; PG8_MMA(0, 0, At, B0); PG8_MMA(0, 1, At, B1); PG8_BAR; PG8_SCHED;
;             PG8_LDA(At, 0, 1); PG8_STAGE(PG8_SB(0, 0), b2, voffB); PG8_STAGE(PG8_SB(0, 1), b2 + hstep, voffB); PG8_STAGE(PG8_SA(0, 0), a2, voffA);
;             PG8_WAIT_V_SEL(relax);
;             PG8_WAIT_L(0); PG8_BAR; PG8_MMA(1, 0, At, B0); PG8_MMA(1, 1, At, B1); PG8_BAR; PG8_SCHED;
.LBB0_596:
	s_add_u32 s0, s74, 0xfff80080
	s_addc_u32 s1, s75, -1
	s_add_i32 s83, 0, 0x10000
	s_cmp_eq_u32 s82, 28
	s_cselect_b32 s79, s40, s1
	s_cselect_b32 s78, s41, s0
	s_cselect_b32 s77, s65, s81
	s_cselect_b32 s76, s73, s80
	s_add_i32 s84, 0, 0x14000
	ds_read_b128 v[150:153], v180
	ds_read_b128 v[154:157], v180 offset:1024
	ds_read_b128 v[158:161], v180 offset:2048
	ds_read_b128 v[162:165], v180 offset:3072
	ds_read_b128 v[166:169], v180 offset:16384
	ds_read_b128 v[172:175], v180 offset:17408
	ds_read_b128 v[176:179], v180 offset:18432
	ds_read_b128 v[188:191], v180 offset:19456
	s_add_i32 m0, s35, 0xc000
	ds_read_b128 v[192:195], v148
	ds_read_b128 v[196:199], v148 offset:1024
	ds_read_b128 v[200:203], v148 offset:2048
	ds_read_b128 v[204:207], v148 offset:3072
	ds_read_b128 v[208:211], v148 offset:4096
	ds_read_b128 v[212:215], v148 offset:5120
	ds_read_b128 v[216:219], v148 offset:6144
	ds_read_b128 v[220:223], v148 offset:7168
	global_load_lds_dwordx4 v140, s[74:75]
	s_add_i32 m0, s35, 0xe000
	s_nop 0
	global_load_lds_dwordx4 v142, s[74:75]
	s_waitcnt vmcnt(8)
	s_waitcnt lgkmcnt(0)
	s_setprio 1
	s_barrier
	v_mfma_f32_16x16x32_bf16 v[126:129], v[150:153], v[192:195], v[126:129]
	v_mfma_f32_16x16x32_bf16 v[126:129], v[154:157], v[196:199], v[126:129]
	v_mfma_f32_16x16x32_bf16 v[122:125], v[150:153], v[200:203], v[122:125]
	v_mfma_f32_16x16x32_bf16 v[122:125], v[154:157], v[204:207], v[122:125]
	v_mfma_f32_16x16x32_bf16 v[118:121], v[150:153], v[208:211], v[118:121]
	v_mfma_f32_16x16x32_bf16 v[118:121], v[154:157], v[212:215], v[118:121]
	v_mfma_f32_16x16x32_bf16 v[114:117], v[150:153], v[216:219], v[114:117]
	v_mfma_f32_16x16x32_bf16 v[114:117], v[154:157], v[220:223], v[114:117]
	v_mfma_f32_16x16x32_bf16 v[98:101], v[158:161], v[216:219], v[98:101]
	v_mfma_f32_16x16x32_bf16 v[98:101], v[162:165], v[220:223], v[98:101]
	v_mfma_f32_16x16x32_bf16 v[102:105], v[158:161], v[208:211], v[102:105]
	v_mfma_f32_16x16x32_bf16 v[102:105], v[162:165], v[212:215], v[102:105]
	v_mfma_f32_16x16x32_bf16 v[106:109], v[158:161], v[200:203], v[106:109]
	v_mfma_f32_16x16x32_bf16 v[106:109], v[162:165], v[204:207], v[106:109]
	v_mfma_f32_16x16x32_bf16 v[110:113], v[158:161], v[192:195], v[110:113]
	v_mfma_f32_16x16x32_bf16 v[110:113], v[162:165], v[196:199], v[110:113]
	v_mfma_f32_16x16x32_bf16 v[70:73], v[166:169], v[192:195], v[70:73]
	v_mfma_f32_16x16x32_bf16 v[70:73], v[172:175], v[196:199], v[70:73]
	v_mfma_f32_16x16x32_bf16 v[66:69], v[166:169], v[200:203], v[66:69]
	v_mfma_f32_16x16x32_bf16 v[66:69], v[172:175], v[204:207], v[66:69]
	v_mfma_f32_16x16x32_bf16 v[58:61], v[166:169], v[208:211], v[58:61]
	v_mfma_f32_16x16x32_bf16 v[58:61], v[172:175], v[212:215], v[58:61]
	v_mfma_f32_16x16x32_bf16 v[46:49], v[166:169], v[216:219], v[46:49]
	v_mfma_f32_16x16x32_bf16 v[46:49], v[172:175], v[220:223], v[46:49]
	v_mfma_f32_16x16x32_bf16 v[34:37], v[176:179], v[216:219], v[34:37]
	v_mfma_f32_16x16x32_bf16 v[34:37], v[188:191], v[220:223], v[34:37]
	v_mfma_f32_16x16x32_bf16 v[38:41], v[176:179], v[208:211], v[38:41]
	v_mfma_f32_16x16x32_bf16 v[38:41], v[188:191], v[212:215], v[38:41]
	v_mfma_f32_16x16x32_bf16 v[42:45], v[176:179], v[200:203], v[42:45]
	v_mfma_f32_16x16x32_bf16 v[42:45], v[188:191], v[204:207], v[42:45]
	v_mfma_f32_16x16x32_bf16 v[50:53], v[176:179], v[192:195], v[50:53]
	v_mfma_f32_16x16x32_bf16 v[50:53], v[188:191], v[196:199], v[50:53]
	s_barrier
	s_setprio 0
	s_add_i32 s0, s83, s20
	s_mov_b32 m0, s0
	ds_read_b128 v[192:195], v148 offset:16384
	ds_read_b128 v[196:199], v148 offset:17408
	ds_read_b128 v[200:203], v148 offset:18432
	ds_read_b128 v[204:207], v148 offset:19456
	ds_read_b128 v[208:211], v148 offset:20480
	ds_read_b128 v[212:215], v148 offset:21504
	ds_read_b128 v[216:219], v148 offset:22528
	ds_read_b128 v[220:223], v148 offset:23552
	global_load_lds_dwordx4 v132, s[76:77]
	s_add_i32 m0, s0, 0x2000
	s_add_u32 s0, s76, 0x80000
	s_addc_u32 s1, s77, 0
	s_add_i32 s83, s84, s20
	global_load_lds_dwordx4 v136, s[76:77]
	s_mov_b32 m0, s83
	s_nop 0
	global_load_lds_dwordx4 v132, s[0:1]
	s_add_i32 m0, s83, 0x2000
	s_nop 0
	global_load_lds_dwordx4 v136, s[0:1]
	s_mov_b32 m0, s35
	s_nop 0
	global_load_lds_dwordx4 v130, s[78:79]
	s_mov_b32 m0, s37
	s_nop 0
	global_load_lds_dwordx4 v134, s[78:79]
	s_waitcnt vmcnt(8)
	s_waitcnt lgkmcnt(0)
	s_setprio 1
	s_barrier
	v_mfma_f32_16x16x32_bf16 v[94:97], v[150:153], v[192:195], v[94:97]
	v_mfma_f32_16x16x32_bf16 v[94:97], v[154:157], v[196:199], v[94:97]
	v_mfma_f32_16x16x32_bf16 v[90:93], v[150:153], v[200:203], v[90:93]
	v_mfma_f32_16x16x32_bf16 v[90:93], v[154:157], v[204:207], v[90:93]
	v_mfma_f32_16x16x32_bf16 v[86:89], v[150:153], v[208:211], v[86:89]
	v_mfma_f32_16x16x32_bf16 v[86:89], v[154:157], v[212:215], v[86:89]
	v_mfma_f32_16x16x32_bf16 v[82:85], v[150:153], v[216:219], v[82:85]
	v_mfma_f32_16x16x32_bf16 v[82:85], v[154:157], v[220:223], v[82:85]
	v_mfma_f32_16x16x32_bf16 v[54:57], v[158:161], v[216:219], v[54:57]
	v_mfma_f32_16x16x32_bf16 v[54:57], v[162:165], v[220:223], v[54:57]
	v_mfma_f32_16x16x32_bf16 v[62:65], v[158:161], v[208:211], v[62:65]
	v_mfma_f32_16x16x32_bf16 v[62:65], v[162:165], v[212:215], v[62:65]
	v_mfma_f32_16x16x32_bf16 v[74:77], v[158:161], v[200:203], v[74:77]
	v_mfma_f32_16x16x32_bf16 v[74:77], v[162:165], v[204:207], v[74:77]
	v_mfma_f32_16x16x32_bf16 v[78:81], v[158:161], v[192:195], v[78:81]
	v_mfma_f32_16x16x32_bf16 v[78:81], v[162:165], v[196:199], v[78:81]
	v_mfma_f32_16x16x32_bf16 v[30:33], v[166:169], v[192:195], v[30:33]
	v_mfma_f32_16x16x32_bf16 v[30:33], v[172:175], v[196:199], v[30:33]
	v_mfma_f32_16x16x32_bf16 v[26:29], v[166:169], v[200:203], v[26:29]
	v_mfma_f32_16x16x32_bf16 v[26:29], v[172:175], v[204:207], v[26:29]
	v_mfma_f32_16x16x32_bf16 v[22:25], v[166:169], v[208:211], v[22:25]
	v_mfma_f32_16x16x32_bf16 v[22:25], v[172:175], v[212:215], v[22:25]
	v_mfma_f32_16x16x32_bf16 v[18:21], v[166:169], v[216:219], v[18:21]
	v_mfma_f32_16x16x32_bf16 v[18:21], v[172:175], v[220:223], v[18:21]
	v_mfma_f32_16x16x32_bf16 v[2:5], v[176:179], v[216:219], v[2:5]
	v_mfma_f32_16x16x32_bf16 v[2:5], v[188:191], v[220:223], v[2:5]
	v_mfma_f32_16x16x32_bf16 v[6:9], v[176:179], v[208:211], v[6:9]
	v_mfma_f32_16x16x32_bf16 v[6:9], v[188:191], v[212:215], v[6:9]
	v_mfma_f32_16x16x32_bf16 v[10:13], v[176:179], v[200:203], v[10:13]
	v_mfma_f32_16x16x32_bf16 v[10:13], v[188:191], v[204:207], v[10:13]
	v_mfma_f32_16x16x32_bf16 v[14:17], v[176:179], v[192:195], v[14:17]
	v_mfma_f32_16x16x32_bf16 v[14:17], v[188:191], v[196:199], v[14:17]
	s_barrier
; #define PG8_STAGE(bufoff, gbase, voff) do { _Pragma("unroll") for (int _i = 0; _i < 2; ++_i) \
;         __builtin_amdgcn_global_load_lds((const unsigned*)((const char*)(gbase) + (voff)[_i]), (PG8_LAS unsigned*)(lds + (bufoff) + ldsw + _i * 8192), 16, 0, 0); } while (0)
; #define PG8_LDA(dst, b, h) do { _Pragma("unroll") for (int m = 0; m < 4; ++m) _Pragma("unroll") for (int k = 0; k < 2; ++k) dst[m][k] = *(const PG8_LAS bf16x8*)(lds + PG8_SA(b, h) + aoff + m * 2048 + k * 1024); } while (0)
; #define PG8_LDB(dst, b, h) do { _Pragma("unroll") for (int n = 0; n < 2; ++n) _Pragma("unroll") for (int k = 0; k < 2; ++k) dst[n][k] = *(const PG8_LAS bf16x8*)(lds + PG8_SB(b, h) + boff + n * 2048 + k * 1024); } while (0)
; #define PG8_WAIT_V(n) asm volatile("s_waitcnt vmcnt(" #n ")" ::: "memory")
; #define PG8_WAIT_L(n) asm volatile("s_waitcnt lgkmcnt(" #n ")" ::: "memory")
; #define PG8_BAR __builtin_amdgcn_s_barrier()
; #define PG8_SCHED __builtin_amdgcn_sched_barrier(0)
;     ...
;             PG8_LDB(B0, 1, 0); PG8_LDB(B1, 1, 1); PG8_SCHED; PG8_LDA(At, 1, 0); PG8_STAGE(PG8_SA(0, 1), a2 + hstep, voffA);
;             PG8_WAIT_V(8); PG8_WAIT_L(0); PG8_BAR; PG8_MMA(0, 0, At, B0); PG8_MMA(0, 1, At, B1); PG8_BAR; PG8_SCHED;
;             PG8_LDA(At, 1, 1); PG8_STAGE(PG8_SB(1, 0), b3, voffB); PG8_STAGE(PG8_SB(1, 1), b3 + hstep, voffB); PG8_STAGE(PG8_SA(1, 0), a3, voffA);
;             PG8_WAIT_V(8); PG8_WAIT_L(0); PG8_BAR; PG8_MMA(1, 0, At, B0); PG8_MMA(1, 1, At, B1); PG8_BAR; PG8_SCHED;
;     ...
;         if constexpr (ALIGN_EPI) { if (wr == 0) PG8_BAR; }
	s_setprio 0
	s_add_i32 s83, 0, 0x18000
	s_add_i32 s84, 0, 0x1c000
	ds_read_b128 v[150:153], v180 offset:32768
	ds_read_b128 v[154:157], v180 offset:33792
	ds_read_b128 v[158:161], v180 offset:34816
	ds_read_b128 v[162:165], v180 offset:35840
	ds_read_b128 v[166:169], v180 offset:49152
	ds_read_b128 v[172:175], v180 offset:50176
	ds_read_b128 v[176:179], v180 offset:51200
	ds_read_b128 v[188:191], v180 offset:52224
	s_add_u32 s0, s78, 0x80000
	s_addc_u32 s1, s79, 0
	s_mov_b32 m0, s43
	ds_read_b128 v[192:195], v148 offset:32768
	ds_read_b128 v[196:199], v148 offset:33792
	ds_read_b128 v[200:203], v148 offset:34816
	ds_read_b128 v[204:207], v148 offset:35840
	ds_read_b128 v[208:211], v148 offset:36864
	ds_read_b128 v[212:215], v148 offset:37888
	ds_read_b128 v[216:219], v148 offset:38912
	ds_read_b128 v[220:223], v148 offset:39936
	global_load_lds_dwordx4 v130, s[0:1]
	s_mov_b32 m0, s44
	s_nop 0
	global_load_lds_dwordx4 v134, s[0:1]
	s_waitcnt vmcnt(8)
	s_waitcnt lgkmcnt(0)
	s_setprio 1
	s_barrier
	v_mfma_f32_16x16x32_bf16 v[126:129], v[150:153], v[192:195], v[126:129]
	v_mfma_f32_16x16x32_bf16 v[126:129], v[154:157], v[196:199], v[126:129]
	v_mfma_f32_16x16x32_bf16 v[122:125], v[150:153], v[200:203], v[122:125]
	v_mfma_f32_16x16x32_bf16 v[122:125], v[154:157], v[204:207], v[122:125]
	v_mfma_f32_16x16x32_bf16 v[118:121], v[150:153], v[208:211], v[118:121]
	v_mfma_f32_16x16x32_bf16 v[118:121], v[154:157], v[212:215], v[118:121]
	v_mfma_f32_16x16x32_bf16 v[114:117], v[150:153], v[216:219], v[114:117]
	v_mfma_f32_16x16x32_bf16 v[114:117], v[154:157], v[220:223], v[114:117]
	v_mfma_f32_16x16x32_bf16 v[98:101], v[158:161], v[216:219], v[98:101]
	v_mfma_f32_16x16x32_bf16 v[98:101], v[162:165], v[220:223], v[98:101]
	v_mfma_f32_16x16x32_bf16 v[102:105], v[158:161], v[208:211], v[102:105]
	v_mfma_f32_16x16x32_bf16 v[102:105], v[162:165], v[212:215], v[102:105]
	v_mfma_f32_16x16x32_bf16 v[106:109], v[158:161], v[200:203], v[106:109]
	v_mfma_f32_16x16x32_bf16 v[106:109], v[162:165], v[204:207], v[106:109]
	v_mfma_f32_16x16x32_bf16 v[110:113], v[158:161], v[192:195], v[110:113]
	v_mfma_f32_16x16x32_bf16 v[110:113], v[162:165], v[196:199], v[110:113]
	v_mfma_f32_16x16x32_bf16 v[70:73], v[166:169], v[192:195], v[70:73]
	v_mfma_f32_16x16x32_bf16 v[70:73], v[172:175], v[196:199], v[70:73]
	v_mfma_f32_16x16x32_bf16 v[66:69], v[166:169], v[200:203], v[66:69]
	v_mfma_f32_16x16x32_bf16 v[66:69], v[172:175], v[204:207], v[66:69]
	v_mfma_f32_16x16x32_bf16 v[58:61], v[166:169], v[208:211], v[58:61]
	v_mfma_f32_16x16x32_bf16 v[58:61], v[172:175], v[212:215], v[58:61]
	v_mfma_f32_16x16x32_bf16 v[46:49], v[166:169], v[216:219], v[46:49]
	v_mfma_f32_16x16x32_bf16 v[46:49], v[172:175], v[220:223], v[46:49]
	v_mfma_f32_16x16x32_bf16 v[34:37], v[176:179], v[216:219], v[34:37]
	v_mfma_f32_16x16x32_bf16 v[34:37], v[188:191], v[220:223], v[34:37]
	v_mfma_f32_16x16x32_bf16 v[38:41], v[176:179], v[208:211], v[38:41]
	v_mfma_f32_16x16x32_bf16 v[38:41], v[188:191], v[212:215], v[38:41]
	v_mfma_f32_16x16x32_bf16 v[42:45], v[176:179], v[200:203], v[42:45]
	v_mfma_f32_16x16x32_bf16 v[42:45], v[188:191], v[204:207], v[42:45]
	v_mfma_f32_16x16x32_bf16 v[50:53], v[176:179], v[192:195], v[50:53]
	v_mfma_f32_16x16x32_bf16 v[50:53], v[188:191], v[196:199], v[50:53]
	s_barrier
	s_setprio 0
	s_add_i32 s0, s83, s20
	s_mov_b32 m0, s0
	ds_read_b128 v[192:195], v148 offset:49152
	ds_read_b128 v[196:199], v148 offset:50176
	ds_read_b128 v[200:203], v148 offset:51200
	ds_read_b128 v[204:207], v148 offset:52224
	ds_read_b128 v[208:211], v148 offset:53248
	ds_read_b128 v[212:215], v148 offset:54272
	ds_read_b128 v[216:219], v148 offset:55296
	ds_read_b128 v[220:223], v148 offset:56320
	s_add_u32 s100, s76, 0x80
	s_addc_u32 s101, s77, 0
	global_load_lds_dwordx4 v132, s[100:101]
	s_add_i32 m0, s0, 0x2000
	s_add_u32 s0, s76, 0x80080
	s_addc_u32 s1, s77, 0
	s_add_i32 s76, s84, s20
	global_load_lds_dwordx4 v136, s[100:101]
	s_mov_b32 m0, s76
	s_nop 0
	global_load_lds_dwordx4 v132, s[0:1]
	s_add_i32 m0, s76, 0x2000
	s_nop 0
	global_load_lds_dwordx4 v136, s[0:1]
	s_mov_b32 m0, s48
	s_nop 0
	s_add_u32 s100, s78, 0x80
	s_addc_u32 s101, s79, 0
	global_load_lds_dwordx4 v130, s[100:101]
	s_mov_b32 m0, s49
	s_nop 0
	global_load_lds_dwordx4 v134, s[100:101]
	s_waitcnt vmcnt(8)
	s_waitcnt lgkmcnt(0)
	s_setprio 1
	s_barrier
	v_mfma_f32_16x16x32_bf16 v[94:97], v[150:153], v[192:195], v[94:97]
	v_mfma_f32_16x16x32_bf16 v[94:97], v[154:157], v[196:199], v[94:97]
	v_mfma_f32_16x16x32_bf16 v[90:93], v[150:153], v[200:203], v[90:93]
	v_mfma_f32_16x16x32_bf16 v[90:93], v[154:157], v[204:207], v[90:93]
	v_mfma_f32_16x16x32_bf16 v[86:89], v[150:153], v[208:211], v[86:89]
	v_mfma_f32_16x16x32_bf16 v[86:89], v[154:157], v[212:215], v[86:89]
	v_mfma_f32_16x16x32_bf16 v[82:85], v[150:153], v[216:219], v[82:85]
	v_mfma_f32_16x16x32_bf16 v[82:85], v[154:157], v[220:223], v[82:85]
	v_mfma_f32_16x16x32_bf16 v[54:57], v[158:161], v[216:219], v[54:57]
	v_mfma_f32_16x16x32_bf16 v[54:57], v[162:165], v[220:223], v[54:57]
	v_mfma_f32_16x16x32_bf16 v[62:65], v[158:161], v[208:211], v[62:65]
	v_mfma_f32_16x16x32_bf16 v[62:65], v[162:165], v[212:215], v[62:65]
	v_mfma_f32_16x16x32_bf16 v[74:77], v[158:161], v[200:203], v[74:77]
	v_mfma_f32_16x16x32_bf16 v[74:77], v[162:165], v[204:207], v[74:77]
	v_mfma_f32_16x16x32_bf16 v[78:81], v[158:161], v[192:195], v[78:81]
	v_mfma_f32_16x16x32_bf16 v[78:81], v[162:165], v[196:199], v[78:81]
	v_mfma_f32_16x16x32_bf16 v[30:33], v[166:169], v[192:195], v[30:33]
	v_mfma_f32_16x16x32_bf16 v[30:33], v[172:175], v[196:199], v[30:33]
	v_mfma_f32_16x16x32_bf16 v[26:29], v[166:169], v[200:203], v[26:29]
	v_mfma_f32_16x16x32_bf16 v[26:29], v[172:175], v[204:207], v[26:29]
	v_mfma_f32_16x16x32_bf16 v[22:25], v[166:169], v[208:211], v[22:25]
	v_mfma_f32_16x16x32_bf16 v[22:25], v[172:175], v[212:215], v[22:25]
	v_mfma_f32_16x16x32_bf16 v[18:21], v[166:169], v[216:219], v[18:21]
	v_mfma_f32_16x16x32_bf16 v[18:21], v[172:175], v[220:223], v[18:21]
	v_mfma_f32_16x16x32_bf16 v[2:5], v[176:179], v[216:219], v[2:5]
	v_mfma_f32_16x16x32_bf16 v[2:5], v[188:191], v[220:223], v[2:5]
	v_mfma_f32_16x16x32_bf16 v[6:9], v[176:179], v[208:211], v[6:9]
	v_mfma_f32_16x16x32_bf16 v[6:9], v[188:191], v[212:215], v[6:9]
	v_mfma_f32_16x16x32_bf16 v[10:13], v[176:179], v[200:203], v[10:13]
	v_mfma_f32_16x16x32_bf16 v[10:13], v[188:191], v[204:207], v[10:13]
	v_mfma_f32_16x16x32_bf16 v[14:17], v[176:179], v[192:195], v[14:17]
	v_mfma_f32_16x16x32_bf16 v[14:17], v[188:191], v[196:199], v[14:17]
	s_barrier
	s_setprio 0
	s_add_i32 s82, s82, 2
	s_add_u32 s74, s74, 0x100
	s_addc_u32 s75, s75, 0
	s_add_u32 s80, s80, 0x100
	s_addc_u32 s81, s81, 0
	s_cmp_gt_u32 s82, 29
	s_cbranch_scc0 .LBB0_596
	s_and_b64 vcc, exec, s[62:63]
	s_cbranch_vccz .LBB0_599
	s_barrier

; #define PG8_STAGE(bufoff, gbase, voff) do { _Pragma("unroll") for (int _i = 0; _i < 2; ++_i) \
;         __builtin_amdgcn_global_load_lds((const unsigned*)((const char*)(gbase) + (voff)[_i]), (PG8_LAS unsigned*)(lds + (bufoff) + ldsw + _i * 8192), 16, 0, 0); } while (0)
; #define PG8_LDA(dst, b, h) do { _Pragma("unroll") for (int m = 0; m < 4; ++m) _Pragma("unroll") for (int k = 0; k < 2; ++k) dst[m][k] = *(const PG8_LAS bf16x8*)(lds + PG8_SA(b, h) + aoff + m * 2048 + k * 1024); } while (0)
; #define PG8_LDB(dst, b, h) do { _Pragma("unroll") for (int n = 0; n < 2; ++n) _Pragma("unroll") for (int k = 0; k < 2; ++k) dst[n][k] = *(const PG8_LAS bf16x8*)(lds + PG8_SB(b, h) + boff + n * 2048 + k * 1024); } while (0)
; #define PG8_WAIT_L(n) asm volatile("s_waitcnt lgkmcnt(" #n ")" ::: "memory")
; #define PG8_WAIT_V_SEL(sel) asm volatile("s_cmp_eq_u32 %0, 0\n\ts_cbranch_scc1 .Lw8_%=\n\ts_waitcnt vmcnt(22)\n\ts_branch .Lwd_%=\n.Lw8_%=:\n\ts_waitcnt vmcnt(8)\n.Lwd_%=:" :: "s"(sel) : "memory", "scc")
; #define PG8_BAR __builtin_amdgcn_s_barrier()
; #define PG8_SCHED __builtin_amdgcn_sched_barrier(0)
;     ...
;         for (int t = 0; t < nt * KREP; t += 2) {
;             const bool last = (t == nt * KREP - 2);
;             const int t1w = KREP > 1 ? ((t + 1) & (nt - 1)) : t + 1, t2w = KREP > 1 ? ((t + 2) & (nt - 1)) : t + 2;
;             const char* a1 = cA + (size_t)t1w * kstep;
;             const char* a2 = last ? nA : cA + (size_t)t2w * kstep; const char* b2 = last ? nB : cB + (size_t)t2w * kstep;
;             const char* a3 = a2 + kstep; const char* b3 = b2 + kstep;
;             if (last && has_next) S.a_ready(nxt);
;             const int relax = __builtin_amdgcn_readfirstlane((MK_RELAXW && t == 0 && ui > 0) ? 1 : 0);
;             if constexpr (SP2) {
;             PG8_LDB(B0, 0, 0); PG8_LDB(B1, 0, 1); PG8_SCHED; PG8_LDA(At, 0, 0); PG8_STAGE(PG8_SA(1, 1), a1 + hstep, voffA);
;             PG8_WAIT_V_SEL(relax);
;             PG8_WAIT_L(0); PG8_BAR; PG8_MMA(0, 0, At, B0); PG8_MMA(0, 1, At, B1); PG8_BAR; PG8_SCHED;
;             PG8_LDA(At, 0, 1); PG8_STAGE(PG8_SB(0, 0), b2, voffB); PG8_STAGE(PG8_SB(0, 1), b2 + hstep, voffB); PG8_STAGE(PG8_SA(0, 0), a2, voffA);
;             PG8_WAIT_V_SEL(relax);
;             PG8_WAIT_L(0); PG8_BAR; PG8_MMA(1, 0, At, B0); PG8_MMA(1, 1, At, B1); PG8_BAR; PG8_SCHED;
.LBB0_1170:
	s_add_u32 s0, s78, 0xfff80080
	s_addc_u32 s1, s79, -1
	s_add_i32 s85, 0, 0x10000
	s_cmp_eq_u32 s84, 28
	s_cselect_b32 s83, s40, s1
	s_cselect_b32 s82, s41, s0
	s_cselect_b32 s81, s67, s77
	s_cselect_b32 s80, s69, s75
	s_add_i32 s86, 0, 0x14000
	ds_read_b128 v[90:93], v184
	ds_read_b128 v[94:97], v184 offset:1024
	ds_read_b128 v[98:101], v184 offset:2048
	ds_read_b128 v[102:105], v184 offset:3072
	ds_read_b128 v[146:149], v184 offset:16384
	ds_read_b128 v[150:153], v184 offset:17408
	ds_read_b128 v[154:157], v184 offset:18432
	ds_read_b128 v[158:161], v184 offset:19456
	s_add_i32 m0, s45, 0xc000
	ds_read_b128 v[162:165], v227
	ds_read_b128 v[166:169], v227 offset:1024
	ds_read_b128 v[188:191], v227 offset:2048
	ds_read_b128 v[192:195], v227 offset:3072
	ds_read_b128 v[196:199], v227 offset:4096
	ds_read_b128 v[200:203], v227 offset:5120
	ds_read_b128 v[204:207], v227 offset:6144
	ds_read_b128 v[208:211], v227 offset:7168
	global_load_lds_dwordx4 v178, s[78:79]
	s_add_i32 m0, s45, 0xe000
	s_nop 0
	global_load_lds_dwordx4 v180, s[78:79]
	s_waitcnt vmcnt(8)
	s_waitcnt lgkmcnt(0)
	s_setprio 1
	s_barrier
	v_mfma_f32_16x16x32_bf16 v[142:145], v[90:93], v[162:165], v[142:145]
	v_mfma_f32_16x16x32_bf16 v[142:145], v[94:97], v[166:169], v[142:145]
	v_mfma_f32_16x16x32_bf16 v[126:129], v[90:93], v[188:191], v[126:129]
	v_mfma_f32_16x16x32_bf16 v[126:129], v[94:97], v[192:195], v[126:129]
	v_mfma_f32_16x16x32_bf16 v[110:113], v[90:93], v[196:199], v[110:113]
	v_mfma_f32_16x16x32_bf16 v[110:113], v[94:97], v[200:203], v[110:113]
	v_mfma_f32_16x16x32_bf16 v[78:81], v[90:93], v[204:207], v[78:81]
	v_mfma_f32_16x16x32_bf16 v[78:81], v[94:97], v[208:211], v[78:81]
	v_mfma_f32_16x16x32_bf16 v[74:77], v[98:101], v[204:207], v[74:77]
	v_mfma_f32_16x16x32_bf16 v[74:77], v[102:105], v[208:211], v[74:77]
	v_mfma_f32_16x16x32_bf16 v[106:109], v[98:101], v[196:199], v[106:109]
	v_mfma_f32_16x16x32_bf16 v[106:109], v[102:105], v[200:203], v[106:109]
	v_mfma_f32_16x16x32_bf16 v[122:125], v[98:101], v[188:191], v[122:125]
	v_mfma_f32_16x16x32_bf16 v[122:125], v[102:105], v[192:195], v[122:125]
	v_mfma_f32_16x16x32_bf16 v[138:141], v[98:101], v[162:165], v[138:141]
	v_mfma_f32_16x16x32_bf16 v[138:141], v[102:105], v[166:169], v[138:141]
	v_mfma_f32_16x16x32_bf16 v[134:137], v[146:149], v[162:165], v[134:137]
	v_mfma_f32_16x16x32_bf16 v[134:137], v[150:153], v[166:169], v[134:137]
	v_mfma_f32_16x16x32_bf16 v[118:121], v[146:149], v[188:191], v[118:121]
	v_mfma_f32_16x16x32_bf16 v[118:121], v[150:153], v[192:195], v[118:121]
	v_mfma_f32_16x16x32_bf16 v[86:89], v[146:149], v[196:199], v[86:89]
	v_mfma_f32_16x16x32_bf16 v[86:89], v[150:153], v[200:203], v[86:89]
	v_mfma_f32_16x16x32_bf16 v[70:73], v[146:149], v[204:207], v[70:73]
	v_mfma_f32_16x16x32_bf16 v[70:73], v[150:153], v[208:211], v[70:73]
	v_mfma_f32_16x16x32_bf16 v[66:69], v[154:157], v[204:207], v[66:69]
	v_mfma_f32_16x16x32_bf16 v[66:69], v[158:161], v[208:211], v[66:69]
	v_mfma_f32_16x16x32_bf16 v[82:85], v[154:157], v[196:199], v[82:85]
	v_mfma_f32_16x16x32_bf16 v[82:85], v[158:161], v[200:203], v[82:85]
	v_mfma_f32_16x16x32_bf16 v[114:117], v[154:157], v[188:191], v[114:117]
	v_mfma_f32_16x16x32_bf16 v[114:117], v[158:161], v[192:195], v[114:117]
	v_mfma_f32_16x16x32_bf16 v[130:133], v[154:157], v[162:165], v[130:133]
	v_mfma_f32_16x16x32_bf16 v[130:133], v[158:161], v[166:169], v[130:133]
	s_barrier
	s_setprio 0
	s_add_i32 s0, s85, s33
	s_mov_b32 m0, s0
	ds_read_b128 v[162:165], v227 offset:16384
	ds_read_b128 v[166:169], v227 offset:17408
	ds_read_b128 v[188:191], v227 offset:18432
	ds_read_b128 v[192:195], v227 offset:19456
	ds_read_b128 v[196:199], v227 offset:20480
	ds_read_b128 v[200:203], v227 offset:21504
	ds_read_b128 v[204:207], v227 offset:22528
	ds_read_b128 v[208:211], v227 offset:23552
	global_load_lds_dwordx4 v182, s[80:81]
	s_add_i32 m0, s0, 0x2000
	s_add_u32 s0, s80, 0x80000
	s_addc_u32 s1, s81, 0
	s_add_i32 s85, s86, s33
	global_load_lds_dwordx4 v176, s[80:81]
	s_mov_b32 m0, s85
	s_nop 0
	global_load_lds_dwordx4 v182, s[0:1]
	s_add_i32 m0, s85, 0x2000
	s_nop 0
	global_load_lds_dwordx4 v176, s[0:1]
	s_mov_b32 m0, s45
	s_nop 0
	global_load_lds_dwordx4 v172, s[82:83]
	s_mov_b32 m0, s46
	s_nop 0
	global_load_lds_dwordx4 v174, s[82:83]
	s_waitcnt vmcnt(8)
	s_waitcnt lgkmcnt(0)
	s_setprio 1
	s_barrier
	v_mfma_f32_16x16x32_bf16 v[62:65], v[90:93], v[162:165], v[62:65]
	v_mfma_f32_16x16x32_bf16 v[62:65], v[94:97], v[166:169], v[62:65]
	v_mfma_f32_16x16x32_bf16 v[46:49], v[90:93], v[188:191], v[46:49]
	v_mfma_f32_16x16x32_bf16 v[46:49], v[94:97], v[192:195], v[46:49]
	v_mfma_f32_16x16x32_bf16 v[30:33], v[90:93], v[196:199], v[30:33]
	v_mfma_f32_16x16x32_bf16 v[30:33], v[94:97], v[200:203], v[30:33]
	v_mfma_f32_16x16x32_bf16 v[14:17], v[90:93], v[204:207], v[14:17]
	v_mfma_f32_16x16x32_bf16 v[14:17], v[94:97], v[208:211], v[14:17]
	v_mfma_f32_16x16x32_bf16 v[10:13], v[98:101], v[204:207], v[10:13]
	v_mfma_f32_16x16x32_bf16 v[10:13], v[102:105], v[208:211], v[10:13]
	v_mfma_f32_16x16x32_bf16 v[26:29], v[98:101], v[196:199], v[26:29]
	v_mfma_f32_16x16x32_bf16 v[26:29], v[102:105], v[200:203], v[26:29]
	v_mfma_f32_16x16x32_bf16 v[42:45], v[98:101], v[188:191], v[42:45]
	v_mfma_f32_16x16x32_bf16 v[42:45], v[102:105], v[192:195], v[42:45]
	v_mfma_f32_16x16x32_bf16 v[58:61], v[98:101], v[162:165], v[58:61]
	v_mfma_f32_16x16x32_bf16 v[58:61], v[102:105], v[166:169], v[58:61]
	v_mfma_f32_16x16x32_bf16 v[54:57], v[146:149], v[162:165], v[54:57]
	v_mfma_f32_16x16x32_bf16 v[54:57], v[150:153], v[166:169], v[54:57]
	v_mfma_f32_16x16x32_bf16 v[38:41], v[146:149], v[188:191], v[38:41]
	v_mfma_f32_16x16x32_bf16 v[38:41], v[150:153], v[192:195], v[38:41]
	v_mfma_f32_16x16x32_bf16 v[22:25], v[146:149], v[196:199], v[22:25]
	v_mfma_f32_16x16x32_bf16 v[22:25], v[150:153], v[200:203], v[22:25]
	v_mfma_f32_16x16x32_bf16 v[6:9], v[146:149], v[204:207], v[6:9]
	v_mfma_f32_16x16x32_bf16 v[6:9], v[150:153], v[208:211], v[6:9]
	v_mfma_f32_16x16x32_bf16 v[2:5], v[154:157], v[204:207], v[2:5]
	v_mfma_f32_16x16x32_bf16 v[2:5], v[158:161], v[208:211], v[2:5]
	v_mfma_f32_16x16x32_bf16 v[18:21], v[154:157], v[196:199], v[18:21]
	v_mfma_f32_16x16x32_bf16 v[18:21], v[158:161], v[200:203], v[18:21]
	v_mfma_f32_16x16x32_bf16 v[34:37], v[154:157], v[188:191], v[34:37]
	v_mfma_f32_16x16x32_bf16 v[34:37], v[158:161], v[192:195], v[34:37]
	v_mfma_f32_16x16x32_bf16 v[50:53], v[154:157], v[162:165], v[50:53]
	v_mfma_f32_16x16x32_bf16 v[50:53], v[158:161], v[166:169], v[50:53]
	s_barrier
; #define PG8_STAGE(bufoff, gbase, voff) do { _Pragma("unroll") for (int _i = 0; _i < 2; ++_i) \
;         __builtin_amdgcn_global_load_lds((const unsigned*)((const char*)(gbase) + (voff)[_i]), (PG8_LAS unsigned*)(lds + (bufoff) + ldsw + _i * 8192), 16, 0, 0); } while (0)
; #define PG8_LDA(dst, b, h) do { _Pragma("unroll") for (int m = 0; m < 4; ++m) _Pragma("unroll") for (int k = 0; k < 2; ++k) dst[m][k] = *(const PG8_LAS bf16x8*)(lds + PG8_SA(b, h) + aoff + m * 2048 + k * 1024); } while (0)
; #define PG8_LDB(dst, b, h) do { _Pragma("unroll") for (int n = 0; n < 2; ++n) _Pragma("unroll") for (int k = 0; k < 2; ++k) dst[n][k] = *(const PG8_LAS bf16x8*)(lds + PG8_SB(b, h) + boff + n * 2048 + k * 1024); } while (0)
; #define PG8_WAIT_V(n) asm volatile("s_waitcnt vmcnt(" #n ")" ::: "memory")
; #define PG8_WAIT_L(n) asm volatile("s_waitcnt lgkmcnt(" #n ")" ::: "memory")
; #define PG8_BAR __builtin_amdgcn_s_barrier()
; #define PG8_SCHED __builtin_amdgcn_sched_barrier(0)
;     ...
;             PG8_LDB(B0, 1, 0); PG8_LDB(B1, 1, 1); PG8_SCHED; PG8_LDA(At, 1, 0); PG8_STAGE(PG8_SA(0, 1), a2 + hstep, voffA);
;             PG8_WAIT_V(8); PG8_WAIT_L(0); PG8_BAR; PG8_MMA(0, 0, At, B0); PG8_MMA(0, 1, At, B1); PG8_BAR; PG8_SCHED;
;             PG8_LDA(At, 1, 1); PG8_STAGE(PG8_SB(1, 0), b3, voffB); PG8_STAGE(PG8_SB(1, 1), b3 + hstep, voffB); PG8_STAGE(PG8_SA(1, 0), a3, voffA);
;             PG8_WAIT_V(8); PG8_WAIT_L(0); PG8_BAR; PG8_MMA(1, 0, At, B0); PG8_MMA(1, 1, At, B1); PG8_BAR; PG8_SCHED;
;     ...
;         if constexpr (ALIGN_EPI) { if (wr == 0) PG8_BAR; }
	s_setprio 0
	s_add_i32 s85, 0, 0x18000
	s_add_i32 s86, 0, 0x1c000
	ds_read_b128 v[90:93], v184 offset:32768
	ds_read_b128 v[94:97], v184 offset:33792
	ds_read_b128 v[98:101], v184 offset:34816
	ds_read_b128 v[102:105], v184 offset:35840
	ds_read_b128 v[146:149], v184 offset:49152
	ds_read_b128 v[150:153], v184 offset:50176
	ds_read_b128 v[154:157], v184 offset:51200
	ds_read_b128 v[158:161], v184 offset:52224
	s_add_u32 s0, s82, 0x80000
	s_addc_u32 s1, s83, 0
	s_mov_b32 m0, s47
	ds_read_b128 v[162:165], v227 offset:32768
	ds_read_b128 v[166:169], v227 offset:33792
	ds_read_b128 v[188:191], v227 offset:34816
	ds_read_b128 v[192:195], v227 offset:35840
	ds_read_b128 v[196:199], v227 offset:36864
	ds_read_b128 v[200:203], v227 offset:37888
	ds_read_b128 v[204:207], v227 offset:38912
	ds_read_b128 v[208:211], v227 offset:39936
	global_load_lds_dwordx4 v172, s[0:1]
	s_mov_b32 m0, s48
	s_nop 0
	global_load_lds_dwordx4 v174, s[0:1]
	s_waitcnt vmcnt(8)
	s_waitcnt lgkmcnt(0)
	s_setprio 1
	s_barrier
	v_mfma_f32_16x16x32_bf16 v[142:145], v[90:93], v[162:165], v[142:145]
	v_mfma_f32_16x16x32_bf16 v[142:145], v[94:97], v[166:169], v[142:145]
	v_mfma_f32_16x16x32_bf16 v[126:129], v[90:93], v[188:191], v[126:129]
	v_mfma_f32_16x16x32_bf16 v[126:129], v[94:97], v[192:195], v[126:129]
	v_mfma_f32_16x16x32_bf16 v[110:113], v[90:93], v[196:199], v[110:113]
	v_mfma_f32_16x16x32_bf16 v[110:113], v[94:97], v[200:203], v[110:113]
	v_mfma_f32_16x16x32_bf16 v[78:81], v[90:93], v[204:207], v[78:81]
	v_mfma_f32_16x16x32_bf16 v[78:81], v[94:97], v[208:211], v[78:81]
	v_mfma_f32_16x16x32_bf16 v[74:77], v[98:101], v[204:207], v[74:77]
	v_mfma_f32_16x16x32_bf16 v[74:77], v[102:105], v[208:211], v[74:77]
	v_mfma_f32_16x16x32_bf16 v[106:109], v[98:101], v[196:199], v[106:109]
	v_mfma_f32_16x16x32_bf16 v[106:109], v[102:105], v[200:203], v[106:109]
	v_mfma_f32_16x16x32_bf16 v[122:125], v[98:101], v[188:191], v[122:125]
	v_mfma_f32_16x16x32_bf16 v[122:125], v[102:105], v[192:195], v[122:125]
	v_mfma_f32_16x16x32_bf16 v[138:141], v[98:101], v[162:165], v[138:141]
	v_mfma_f32_16x16x32_bf16 v[138:141], v[102:105], v[166:169], v[138:141]
	v_mfma_f32_16x16x32_bf16 v[134:137], v[146:149], v[162:165], v[134:137]
	v_mfma_f32_16x16x32_bf16 v[134:137], v[150:153], v[166:169], v[134:137]
	v_mfma_f32_16x16x32_bf16 v[118:121], v[146:149], v[188:191], v[118:121]
	v_mfma_f32_16x16x32_bf16 v[118:121], v[150:153], v[192:195], v[118:121]
	v_mfma_f32_16x16x32_bf16 v[86:89], v[146:149], v[196:199], v[86:89]
	v_mfma_f32_16x16x32_bf16 v[86:89], v[150:153], v[200:203], v[86:89]
	v_mfma_f32_16x16x32_bf16 v[70:73], v[146:149], v[204:207], v[70:73]
	v_mfma_f32_16x16x32_bf16 v[70:73], v[150:153], v[208:211], v[70:73]
	v_mfma_f32_16x16x32_bf16 v[66:69], v[154:157], v[204:207], v[66:69]
	v_mfma_f32_16x16x32_bf16 v[66:69], v[158:161], v[208:211], v[66:69]
	v_mfma_f32_16x16x32_bf16 v[82:85], v[154:157], v[196:199], v[82:85]
	v_mfma_f32_16x16x32_bf16 v[82:85], v[158:161], v[200:203], v[82:85]
	v_mfma_f32_16x16x32_bf16 v[114:117], v[154:157], v[188:191], v[114:117]
	v_mfma_f32_16x16x32_bf16 v[114:117], v[158:161], v[192:195], v[114:117]
	v_mfma_f32_16x16x32_bf16 v[130:133], v[154:157], v[162:165], v[130:133]
	v_mfma_f32_16x16x32_bf16 v[130:133], v[158:161], v[166:169], v[130:133]
	s_barrier
	s_setprio 0
	s_add_i32 s0, s85, s33
	s_mov_b32 m0, s0
	ds_read_b128 v[162:165], v227 offset:49152
	ds_read_b128 v[166:169], v227 offset:50176
	ds_read_b128 v[188:191], v227 offset:51200
	ds_read_b128 v[192:195], v227 offset:52224
	ds_read_b128 v[196:199], v227 offset:53248
	ds_read_b128 v[200:203], v227 offset:54272
	ds_read_b128 v[204:207], v227 offset:55296
	ds_read_b128 v[208:211], v227 offset:56320
	s_add_u32 s100, s80, 0x80
	s_addc_u32 s101, s81, 0
	global_load_lds_dwordx4 v182, s[100:101]
	s_add_i32 m0, s0, 0x2000
	s_add_u32 s0, s80, 0x80080
	s_addc_u32 s1, s81, 0
	s_add_i32 s80, s86, s33
	global_load_lds_dwordx4 v176, s[100:101]
	s_mov_b32 m0, s80
	s_nop 0
	global_load_lds_dwordx4 v182, s[0:1]
	s_add_i32 m0, s80, 0x2000
	s_nop 0
	global_load_lds_dwordx4 v176, s[0:1]
	s_mov_b32 m0, s50
	s_nop 0
	s_add_u32 s100, s82, 0x80
	s_addc_u32 s101, s83, 0
	global_load_lds_dwordx4 v172, s[100:101]
	s_mov_b32 m0, s51
	s_nop 0
	global_load_lds_dwordx4 v174, s[100:101]
	s_waitcnt vmcnt(8)
	s_waitcnt lgkmcnt(0)
	s_setprio 1
	s_barrier
	v_mfma_f32_16x16x32_bf16 v[62:65], v[90:93], v[162:165], v[62:65]
	v_mfma_f32_16x16x32_bf16 v[62:65], v[94:97], v[166:169], v[62:65]
	v_mfma_f32_16x16x32_bf16 v[46:49], v[90:93], v[188:191], v[46:49]
	v_mfma_f32_16x16x32_bf16 v[46:49], v[94:97], v[192:195], v[46:49]
	v_mfma_f32_16x16x32_bf16 v[30:33], v[90:93], v[196:199], v[30:33]
	v_mfma_f32_16x16x32_bf16 v[30:33], v[94:97], v[200:203], v[30:33]
	v_mfma_f32_16x16x32_bf16 v[14:17], v[90:93], v[204:207], v[14:17]
	v_mfma_f32_16x16x32_bf16 v[14:17], v[94:97], v[208:211], v[14:17]
	v_mfma_f32_16x16x32_bf16 v[10:13], v[98:101], v[204:207], v[10:13]
	v_mfma_f32_16x16x32_bf16 v[10:13], v[102:105], v[208:211], v[10:13]
	v_mfma_f32_16x16x32_bf16 v[26:29], v[98:101], v[196:199], v[26:29]
	v_mfma_f32_16x16x32_bf16 v[26:29], v[102:105], v[200:203], v[26:29]
	v_mfma_f32_16x16x32_bf16 v[42:45], v[98:101], v[188:191], v[42:45]
	v_mfma_f32_16x16x32_bf16 v[42:45], v[102:105], v[192:195], v[42:45]
	v_mfma_f32_16x16x32_bf16 v[58:61], v[98:101], v[162:165], v[58:61]
	v_mfma_f32_16x16x32_bf16 v[58:61], v[102:105], v[166:169], v[58:61]
	v_mfma_f32_16x16x32_bf16 v[54:57], v[146:149], v[162:165], v[54:57]
	v_mfma_f32_16x16x32_bf16 v[54:57], v[150:153], v[166:169], v[54:57]
	v_mfma_f32_16x16x32_bf16 v[38:41], v[146:149], v[188:191], v[38:41]
	v_mfma_f32_16x16x32_bf16 v[38:41], v[150:153], v[192:195], v[38:41]
	v_mfma_f32_16x16x32_bf16 v[22:25], v[146:149], v[196:199], v[22:25]
	v_mfma_f32_16x16x32_bf16 v[22:25], v[150:153], v[200:203], v[22:25]
	v_mfma_f32_16x16x32_bf16 v[6:9], v[146:149], v[204:207], v[6:9]
	v_mfma_f32_16x16x32_bf16 v[6:9], v[150:153], v[208:211], v[6:9]
	v_mfma_f32_16x16x32_bf16 v[2:5], v[154:157], v[204:207], v[2:5]
	v_mfma_f32_16x16x32_bf16 v[2:5], v[158:161], v[208:211], v[2:5]
	v_mfma_f32_16x16x32_bf16 v[18:21], v[154:157], v[196:199], v[18:21]
	v_mfma_f32_16x16x32_bf16 v[18:21], v[158:161], v[200:203], v[18:21]
	v_mfma_f32_16x16x32_bf16 v[34:37], v[154:157], v[188:191], v[34:37]
	v_mfma_f32_16x16x32_bf16 v[34:37], v[158:161], v[192:195], v[34:37]
	v_mfma_f32_16x16x32_bf16 v[50:53], v[154:157], v[162:165], v[50:53]
	v_mfma_f32_16x16x32_bf16 v[50:53], v[158:161], v[166:169], v[50:53]
	s_barrier
	s_setprio 0
	s_add_i32 s84, s84, 2
	s_add_u32 s78, s78, 0x100
	s_addc_u32 s79, s79, 0
	s_add_u32 s75, s75, 0x100
	s_addc_u32 s77, s77, 0
	s_cmp_gt_u32 s84, 29
	s_cbranch_scc0 .LBB0_1170
	s_and_b64 vcc, exec, s[64:65]
	s_cbranch_vccz .LBB0_1173
	s_barrier

; #define PG8_STAGE(bufoff, gbase, voff) do { _Pragma("unroll") for (int _i = 0; _i < 2; ++_i) \
;         __builtin_amdgcn_global_load_lds((const unsigned*)((const char*)(gbase) + (voff)[_i]), (PG8_LAS unsigned*)(lds + (bufoff) + ldsw + _i * 8192), 16, 0, 0); } while (0)
; #define PG8_LDA(dst, b, h) do { _Pragma("unroll") for (int m = 0; m < 4; ++m) _Pragma("unroll") for (int k = 0; k < 2; ++k) dst[m][k] = *(const PG8_LAS bf16x8*)(lds + PG8_SA(b, h) + aoff + m * 2048 + k * 1024); } while (0)
; #define PG8_LDB(dst, b, h) do { _Pragma("unroll") for (int n = 0; n < 2; ++n) _Pragma("unroll") for (int k = 0; k < 2; ++k) dst[n][k] = *(const PG8_LAS bf16x8*)(lds + PG8_SB(b, h) + boff + n * 2048 + k * 1024); } while (0)
; #define PG8_WAIT_L(n) asm volatile("s_waitcnt lgkmcnt(" #n ")" ::: "memory")
; #define PG8_WAIT_V_SEL(sel) asm volatile("s_cmp_eq_u32 %0, 0\n\ts_cbranch_scc1 .Lw8_%=\n\ts_waitcnt vmcnt(22)\n\ts_branch .Lwd_%=\n.Lw8_%=:\n\ts_waitcnt vmcnt(8)\n.Lwd_%=:" :: "s"(sel) : "memory", "scc")
; #define PG8_BAR __builtin_amdgcn_s_barrier()
; #define PG8_SCHED __builtin_amdgcn_sched_barrier(0)
;     ...
;         for (int t = 0; t < nt * KREP; t += 2) {
;             const bool last = (t == nt * KREP - 2);
;             const int t1w = KREP > 1 ? ((t + 1) & (nt - 1)) : t + 1, t2w = KREP > 1 ? ((t + 2) & (nt - 1)) : t + 2;
;             const char* a1 = cA + (size_t)t1w * kstep;
;             const char* a2 = last ? nA : cA + (size_t)t2w * kstep; const char* b2 = last ? nB : cB + (size_t)t2w * kstep;
;             const char* a3 = a2 + kstep; const char* b3 = b2 + kstep;
;             if (last && has_next) S.a_ready(nxt);
;             const int relax = __builtin_amdgcn_readfirstlane((MK_RELAXW && t == 0 && ui > 0) ? 1 : 0);
;             if constexpr (SP2) {
;             PG8_LDB(B0, 0, 0); PG8_LDB(B1, 0, 1); PG8_SCHED; PG8_LDA(At, 0, 0); PG8_STAGE(PG8_SA(1, 1), a1 + hstep, voffA);
;             PG8_WAIT_V_SEL(relax);
;             PG8_WAIT_L(0); PG8_BAR; PG8_MMA(0, 0, At, B0); PG8_MMA(0, 1, At, B1); PG8_BAR; PG8_SCHED;
;             PG8_LDA(At, 0, 1); PG8_STAGE(PG8_SB(0, 0), b2, voffB); PG8_STAGE(PG8_SB(0, 1), b2 + hstep, voffB); PG8_STAGE(PG8_SA(0, 0), a2, voffA);
;             PG8_WAIT_V_SEL(relax);
;             PG8_WAIT_L(0); PG8_BAR; PG8_MMA(1, 0, At, B0); PG8_MMA(1, 1, At, B1); PG8_BAR; PG8_SCHED;
.LBB0_1327:
	s_add_u32 s96, s12, 0x100
	s_addc_u32 s97, s13, 0
	s_add_i32 s51, 0, 0x10000
	s_cmp_eq_u32 s0, 28
	s_cselect_b32 s41, s59, s97
	s_cselect_b32 s40, s64, s96
	s_cselect_b32 vcc_hi, s65, s67
	s_cselect_b32 vcc_lo, s87, s66
	s_add_i32 s19, 0, 0x14000
	ds_read_b128 v[66:69], v200
	ds_read_b128 v[70:73], v200 offset:1024
	ds_read_b128 v[82:85], v200 offset:2048
	ds_read_b128 v[142:145], v200 offset:3072
	ds_read_b128 v[146:149], v200 offset:16384
	ds_read_b128 v[150:153], v200 offset:17408
	ds_read_b128 v[154:157], v200 offset:18432
	ds_read_b128 v[158:161], v200 offset:19456
	s_add_i32 m0, s95, 0xc000
	ds_read_b128 v[162:165], v219
	ds_read_b128 v[166:169], v219 offset:1024
	ds_read_b128 v[170:173], v219 offset:2048
	ds_read_b128 v[174:177], v219 offset:3072
	ds_read_b128 v[178:181], v219 offset:4096
	ds_read_b128 v[184:187], v219 offset:5120
	ds_read_b128 v[220:223], v219 offset:6144
	ds_read_b128 v[224:227], v219 offset:7168
	global_load_lds_dwordx4 v196, s[12:13]
	s_add_i32 m0, s95, 0xe000
	s_nop 0
	global_load_lds_dwordx4 v198, s[12:13]
	s_waitcnt vmcnt(8)
	s_waitcnt lgkmcnt(0)
	s_setprio 1
	s_barrier
	v_mfma_f32_16x16x32_bf16 v[114:117], v[66:69], v[162:165], v[114:117]
	v_mfma_f32_16x16x32_bf16 v[114:117], v[70:73], v[166:169], v[114:117]
	v_mfma_f32_16x16x32_bf16 v[110:113], v[66:69], v[170:173], v[110:113]
	v_mfma_f32_16x16x32_bf16 v[110:113], v[70:73], v[174:177], v[110:113]
	v_mfma_f32_16x16x32_bf16 v[78:81], v[66:69], v[178:181], v[78:81]
	v_mfma_f32_16x16x32_bf16 v[78:81], v[70:73], v[184:187], v[78:81]
	v_mfma_f32_16x16x32_bf16 v[74:77], v[66:69], v[220:223], v[74:77]
	v_mfma_f32_16x16x32_bf16 v[74:77], v[70:73], v[224:227], v[74:77]
	v_mfma_f32_16x16x32_bf16 v[134:137], v[82:85], v[220:223], v[134:137]
	v_mfma_f32_16x16x32_bf16 v[134:137], v[142:145], v[224:227], v[134:137]
	v_mfma_f32_16x16x32_bf16 v[138:141], v[82:85], v[178:181], v[138:141]
	v_mfma_f32_16x16x32_bf16 v[138:141], v[142:145], v[184:187], v[138:141]
	v_mfma_f32_16x16x32_bf16 v[102:105], v[82:85], v[170:173], v[102:105]
	v_mfma_f32_16x16x32_bf16 v[102:105], v[142:145], v[174:177], v[102:105]
	v_mfma_f32_16x16x32_bf16 v[106:109], v[82:85], v[162:165], v[106:109]
	v_mfma_f32_16x16x32_bf16 v[106:109], v[142:145], v[166:169], v[106:109]
	v_mfma_f32_16x16x32_bf16 v[98:101], v[146:149], v[162:165], v[98:101]
	v_mfma_f32_16x16x32_bf16 v[98:101], v[150:153], v[166:169], v[98:101]
	v_mfma_f32_16x16x32_bf16 v[94:97], v[146:149], v[170:173], v[94:97]
	v_mfma_f32_16x16x32_bf16 v[94:97], v[150:153], v[174:177], v[94:97]
	v_mfma_f32_16x16x32_bf16 v[130:133], v[146:149], v[178:181], v[130:133]
	v_mfma_f32_16x16x32_bf16 v[130:133], v[150:153], v[184:187], v[130:133]
	v_mfma_f32_16x16x32_bf16 v[126:129], v[146:149], v[220:223], v[126:129]
	v_mfma_f32_16x16x32_bf16 v[126:129], v[150:153], v[224:227], v[126:129]
	v_mfma_f32_16x16x32_bf16 v[118:121], v[154:157], v[220:223], v[118:121]
	v_mfma_f32_16x16x32_bf16 v[118:121], v[158:161], v[224:227], v[118:121]
	v_mfma_f32_16x16x32_bf16 v[122:125], v[154:157], v[178:181], v[122:125]
	v_mfma_f32_16x16x32_bf16 v[122:125], v[158:161], v[184:187], v[122:125]
	v_mfma_f32_16x16x32_bf16 v[86:89], v[154:157], v[170:173], v[86:89]
	v_mfma_f32_16x16x32_bf16 v[86:89], v[158:161], v[174:177], v[86:89]
	v_mfma_f32_16x16x32_bf16 v[90:93], v[154:157], v[162:165], v[90:93]
	v_mfma_f32_16x16x32_bf16 v[90:93], v[158:161], v[166:169], v[90:93]
	s_barrier
	s_setprio 0
	s_add_i32 s12, s51, s37
	s_mov_b32 m0, s12
	ds_read_b128 v[162:165], v219 offset:16384
	ds_read_b128 v[166:169], v219 offset:17408
	ds_read_b128 v[170:173], v219 offset:18432
	ds_read_b128 v[174:177], v219 offset:19456
	ds_read_b128 v[178:181], v219 offset:20480
	ds_read_b128 v[184:187], v219 offset:21504
	ds_read_b128 v[220:223], v219 offset:22528
	ds_read_b128 v[224:227], v219 offset:23552
	global_load_lds_dwordx4 v182, vcc
	s_add_i32 m0, s12, 0x2000
	s_add_u32 s12, vcc_lo, 0x80000
	s_addc_u32 s13, vcc_hi, 0
	s_add_i32 s19, s19, s37
	global_load_lds_dwordx4 v192, vcc
	s_mov_b32 m0, s19
	s_nop 0
	global_load_lds_dwordx4 v182, s[12:13]
	s_add_i32 m0, s19, 0x2000
	s_nop 0
	global_load_lds_dwordx4 v192, s[12:13]
	s_mov_b32 m0, s95
	s_nop 0
	global_load_lds_dwordx4 v188, s[40:41]
	s_mov_b32 m0, s20
	s_nop 0
	global_load_lds_dwordx4 v190, s[40:41]
	s_waitcnt vmcnt(8)
	s_waitcnt lgkmcnt(0)
	s_setprio 1
	s_barrier
	v_mfma_f32_16x16x32_bf16 v[30:33], v[66:69], v[162:165], v[30:33]
	v_mfma_f32_16x16x32_bf16 v[30:33], v[70:73], v[166:169], v[30:33]
	v_mfma_f32_16x16x32_bf16 v[26:29], v[66:69], v[170:173], v[26:29]
	v_mfma_f32_16x16x32_bf16 v[26:29], v[70:73], v[174:177], v[26:29]
	v_mfma_f32_16x16x32_bf16 v[62:65], v[66:69], v[178:181], v[62:65]
	v_mfma_f32_16x16x32_bf16 v[62:65], v[70:73], v[184:187], v[62:65]
	v_mfma_f32_16x16x32_bf16 v[58:61], v[66:69], v[220:223], v[58:61]
	v_mfma_f32_16x16x32_bf16 v[58:61], v[70:73], v[224:227], v[58:61]
	v_mfma_f32_16x16x32_bf16 v[50:53], v[82:85], v[220:223], v[50:53]
	v_mfma_f32_16x16x32_bf16 v[50:53], v[142:145], v[224:227], v[50:53]
	v_mfma_f32_16x16x32_bf16 v[54:57], v[82:85], v[178:181], v[54:57]
	v_mfma_f32_16x16x32_bf16 v[54:57], v[142:145], v[184:187], v[54:57]
	v_mfma_f32_16x16x32_bf16 v[18:21], v[82:85], v[170:173], v[18:21]
	v_mfma_f32_16x16x32_bf16 v[18:21], v[142:145], v[174:177], v[18:21]
	v_mfma_f32_16x16x32_bf16 v[22:25], v[82:85], v[162:165], v[22:25]
	v_mfma_f32_16x16x32_bf16 v[22:25], v[142:145], v[166:169], v[22:25]
	v_mfma_f32_16x16x32_bf16 v[14:17], v[146:149], v[162:165], v[14:17]
	v_mfma_f32_16x16x32_bf16 v[14:17], v[150:153], v[166:169], v[14:17]
	v_mfma_f32_16x16x32_bf16 v[10:13], v[146:149], v[170:173], v[10:13]
	v_mfma_f32_16x16x32_bf16 v[10:13], v[150:153], v[174:177], v[10:13]
	v_mfma_f32_16x16x32_bf16 v[46:49], v[146:149], v[178:181], v[46:49]
	v_mfma_f32_16x16x32_bf16 v[46:49], v[150:153], v[184:187], v[46:49]
	v_mfma_f32_16x16x32_bf16 v[38:41], v[146:149], v[220:223], v[38:41]
	v_mfma_f32_16x16x32_bf16 v[38:41], v[150:153], v[224:227], v[38:41]
	v_mfma_f32_16x16x32_bf16 v[42:45], v[154:157], v[220:223], v[42:45]
	v_mfma_f32_16x16x32_bf16 v[42:45], v[158:161], v[224:227], v[42:45]
	v_mfma_f32_16x16x32_bf16 v[34:37], v[154:157], v[178:181], v[34:37]
	v_mfma_f32_16x16x32_bf16 v[34:37], v[158:161], v[184:187], v[34:37]
	v_mfma_f32_16x16x32_bf16 v[2:5], v[154:157], v[170:173], v[2:5]
	v_mfma_f32_16x16x32_bf16 v[2:5], v[158:161], v[174:177], v[2:5]
	v_mfma_f32_16x16x32_bf16 v[6:9], v[154:157], v[162:165], v[6:9]
	v_mfma_f32_16x16x32_bf16 v[6:9], v[158:161], v[166:169], v[6:9]
	s_barrier
; #define PG8_STAGE(bufoff, gbase, voff) do { _Pragma("unroll") for (int _i = 0; _i < 2; ++_i) \
;         __builtin_amdgcn_global_load_lds((const unsigned*)((const char*)(gbase) + (voff)[_i]), (PG8_LAS unsigned*)(lds + (bufoff) + ldsw + _i * 8192), 16, 0, 0); } while (0)
; #define PG8_LDA(dst, b, h) do { _Pragma("unroll") for (int m = 0; m < 4; ++m) _Pragma("unroll") for (int k = 0; k < 2; ++k) dst[m][k] = *(const PG8_LAS bf16x8*)(lds + PG8_SA(b, h) + aoff + m * 2048 + k * 1024); } while (0)
; #define PG8_LDB(dst, b, h) do { _Pragma("unroll") for (int n = 0; n < 2; ++n) _Pragma("unroll") for (int k = 0; k < 2; ++k) dst[n][k] = *(const PG8_LAS bf16x8*)(lds + PG8_SB(b, h) + boff + n * 2048 + k * 1024); } while (0)
; #define PG8_WAIT_V(n) asm volatile("s_waitcnt vmcnt(" #n ")" ::: "memory")
; #define PG8_WAIT_L(n) asm volatile("s_waitcnt lgkmcnt(" #n ")" ::: "memory")
; #define PG8_BAR __builtin_amdgcn_s_barrier()
; #define PG8_SCHED __builtin_amdgcn_sched_barrier(0)
;     ...
;             PG8_LDB(B0, 1, 0); PG8_LDB(B1, 1, 1); PG8_SCHED; PG8_LDA(At, 1, 0); PG8_STAGE(PG8_SA(0, 1), a2 + hstep, voffA);
;             PG8_WAIT_V(8); PG8_WAIT_L(0); PG8_BAR; PG8_MMA(0, 0, At, B0); PG8_MMA(0, 1, At, B1); PG8_BAR; PG8_SCHED;
;             PG8_LDA(At, 1, 1); PG8_STAGE(PG8_SB(1, 0), b3, voffB); PG8_STAGE(PG8_SB(1, 1), b3 + hstep, voffB); PG8_STAGE(PG8_SA(1, 0), a3, voffA);
;             PG8_WAIT_V(8); PG8_WAIT_L(0); PG8_BAR; PG8_MMA(1, 0, At, B0); PG8_MMA(1, 1, At, B1); PG8_BAR; PG8_SCHED;
;     ...
;         if constexpr (ALIGN_EPI) { if (wr == 0) PG8_BAR; }
	s_setprio 0
	s_add_i32 s19, 0, 0x18000
	s_add_i32 s51, 0, 0x1c000
	ds_read_b128 v[66:69], v200 offset:32768
	ds_read_b128 v[70:73], v200 offset:33792
	ds_read_b128 v[82:85], v200 offset:34816
	ds_read_b128 v[142:145], v200 offset:35840
	ds_read_b128 v[146:149], v200 offset:49152
	ds_read_b128 v[150:153], v200 offset:50176
	ds_read_b128 v[154:157], v200 offset:51200
	ds_read_b128 v[158:161], v200 offset:52224
	s_add_u32 s12, s40, 0x80000
	s_addc_u32 s13, s41, 0
	s_mov_b32 m0, s44
	ds_read_b128 v[162:165], v219 offset:32768
	ds_read_b128 v[166:169], v219 offset:33792
	ds_read_b128 v[170:173], v219 offset:34816
	ds_read_b128 v[174:177], v219 offset:35840
	ds_read_b128 v[178:181], v219 offset:36864
	ds_read_b128 v[184:187], v219 offset:37888
	ds_read_b128 v[220:223], v219 offset:38912
	ds_read_b128 v[224:227], v219 offset:39936
	global_load_lds_dwordx4 v188, s[12:13]
	s_mov_b32 m0, s46
	s_nop 0
	global_load_lds_dwordx4 v190, s[12:13]
	s_waitcnt vmcnt(8)
	s_waitcnt lgkmcnt(0)
	s_setprio 1
	s_barrier
	v_mfma_f32_16x16x32_bf16 v[114:117], v[66:69], v[162:165], v[114:117]
	v_mfma_f32_16x16x32_bf16 v[114:117], v[70:73], v[166:169], v[114:117]
	v_mfma_f32_16x16x32_bf16 v[110:113], v[66:69], v[170:173], v[110:113]
	v_mfma_f32_16x16x32_bf16 v[110:113], v[70:73], v[174:177], v[110:113]
	v_mfma_f32_16x16x32_bf16 v[78:81], v[66:69], v[178:181], v[78:81]
	v_mfma_f32_16x16x32_bf16 v[78:81], v[70:73], v[184:187], v[78:81]
	v_mfma_f32_16x16x32_bf16 v[74:77], v[66:69], v[220:223], v[74:77]
	v_mfma_f32_16x16x32_bf16 v[74:77], v[70:73], v[224:227], v[74:77]
	v_mfma_f32_16x16x32_bf16 v[134:137], v[82:85], v[220:223], v[134:137]
	v_mfma_f32_16x16x32_bf16 v[134:137], v[142:145], v[224:227], v[134:137]
	v_mfma_f32_16x16x32_bf16 v[138:141], v[82:85], v[178:181], v[138:141]
	v_mfma_f32_16x16x32_bf16 v[138:141], v[142:145], v[184:187], v[138:141]
	v_mfma_f32_16x16x32_bf16 v[102:105], v[82:85], v[170:173], v[102:105]
	v_mfma_f32_16x16x32_bf16 v[102:105], v[142:145], v[174:177], v[102:105]
	v_mfma_f32_16x16x32_bf16 v[106:109], v[82:85], v[162:165], v[106:109]
	v_mfma_f32_16x16x32_bf16 v[106:109], v[142:145], v[166:169], v[106:109]
	v_mfma_f32_16x16x32_bf16 v[98:101], v[146:149], v[162:165], v[98:101]
	v_mfma_f32_16x16x32_bf16 v[98:101], v[150:153], v[166:169], v[98:101]
	v_mfma_f32_16x16x32_bf16 v[94:97], v[146:149], v[170:173], v[94:97]
	v_mfma_f32_16x16x32_bf16 v[94:97], v[150:153], v[174:177], v[94:97]
	v_mfma_f32_16x16x32_bf16 v[130:133], v[146:149], v[178:181], v[130:133]
	v_mfma_f32_16x16x32_bf16 v[130:133], v[150:153], v[184:187], v[130:133]
	v_mfma_f32_16x16x32_bf16 v[126:129], v[146:149], v[220:223], v[126:129]
	v_mfma_f32_16x16x32_bf16 v[126:129], v[150:153], v[224:227], v[126:129]
	v_mfma_f32_16x16x32_bf16 v[118:121], v[154:157], v[220:223], v[118:121]
	v_mfma_f32_16x16x32_bf16 v[118:121], v[158:161], v[224:227], v[118:121]
	v_mfma_f32_16x16x32_bf16 v[122:125], v[154:157], v[178:181], v[122:125]
	v_mfma_f32_16x16x32_bf16 v[122:125], v[158:161], v[184:187], v[122:125]
	v_mfma_f32_16x16x32_bf16 v[86:89], v[154:157], v[170:173], v[86:89]
	v_mfma_f32_16x16x32_bf16 v[86:89], v[158:161], v[174:177], v[86:89]
	v_mfma_f32_16x16x32_bf16 v[90:93], v[154:157], v[162:165], v[90:93]
	v_mfma_f32_16x16x32_bf16 v[90:93], v[158:161], v[166:169], v[90:93]
	s_barrier
	s_setprio 0
	s_add_i32 s12, s19, s37
	s_mov_b32 m0, s12
	ds_read_b128 v[162:165], v219 offset:49152
	ds_read_b128 v[166:169], v219 offset:50176
	ds_read_b128 v[170:173], v219 offset:51200
	ds_read_b128 v[174:177], v219 offset:52224
	ds_read_b128 v[178:181], v219 offset:53248
	ds_read_b128 v[184:187], v219 offset:54272
	ds_read_b128 v[220:223], v219 offset:55296
	ds_read_b128 v[224:227], v219 offset:56320
	s_add_u32 s100, vcc_lo, 0x80
	s_addc_u32 s101, vcc_hi, 0
	global_load_lds_dwordx4 v182, s[100:101]
	s_add_i32 m0, s12, 0x2000
	s_add_u32 s12, vcc_lo, 0x80080
	s_addc_u32 s13, vcc_hi, 0
	s_add_i32 s19, s51, s37
	global_load_lds_dwordx4 v192, s[100:101]
	s_mov_b32 m0, s19
	s_nop 0
	global_load_lds_dwordx4 v182, s[12:13]
	s_add_i32 m0, s19, 0x2000
	s_nop 0
	global_load_lds_dwordx4 v192, s[12:13]
	s_mov_b32 m0, s45
	s_nop 0
	s_add_u32 s100, s40, 0x80
	s_addc_u32 s101, s41, 0
	global_load_lds_dwordx4 v188, s[100:101]
	s_mov_b32 m0, s24
	s_nop 0
	global_load_lds_dwordx4 v190, s[100:101]
	s_waitcnt vmcnt(8)
	s_waitcnt lgkmcnt(0)
	s_setprio 1
	s_barrier
	v_mfma_f32_16x16x32_bf16 v[30:33], v[66:69], v[162:165], v[30:33]
	v_mfma_f32_16x16x32_bf16 v[30:33], v[70:73], v[166:169], v[30:33]
	v_mfma_f32_16x16x32_bf16 v[26:29], v[66:69], v[170:173], v[26:29]
	v_mfma_f32_16x16x32_bf16 v[26:29], v[70:73], v[174:177], v[26:29]
	v_mfma_f32_16x16x32_bf16 v[62:65], v[66:69], v[178:181], v[62:65]
	v_mfma_f32_16x16x32_bf16 v[62:65], v[70:73], v[184:187], v[62:65]
	v_mfma_f32_16x16x32_bf16 v[58:61], v[66:69], v[220:223], v[58:61]
	v_mfma_f32_16x16x32_bf16 v[58:61], v[70:73], v[224:227], v[58:61]
	v_mfma_f32_16x16x32_bf16 v[50:53], v[82:85], v[220:223], v[50:53]
	v_mfma_f32_16x16x32_bf16 v[50:53], v[142:145], v[224:227], v[50:53]
	v_mfma_f32_16x16x32_bf16 v[54:57], v[82:85], v[178:181], v[54:57]
	v_mfma_f32_16x16x32_bf16 v[54:57], v[142:145], v[184:187], v[54:57]
	v_mfma_f32_16x16x32_bf16 v[18:21], v[82:85], v[170:173], v[18:21]
	v_mfma_f32_16x16x32_bf16 v[18:21], v[142:145], v[174:177], v[18:21]
	v_mfma_f32_16x16x32_bf16 v[22:25], v[82:85], v[162:165], v[22:25]
	v_mfma_f32_16x16x32_bf16 v[22:25], v[142:145], v[166:169], v[22:25]
	v_mfma_f32_16x16x32_bf16 v[14:17], v[146:149], v[162:165], v[14:17]
	v_mfma_f32_16x16x32_bf16 v[14:17], v[150:153], v[166:169], v[14:17]
	v_mfma_f32_16x16x32_bf16 v[10:13], v[146:149], v[170:173], v[10:13]
	v_mfma_f32_16x16x32_bf16 v[10:13], v[150:153], v[174:177], v[10:13]
	v_mfma_f32_16x16x32_bf16 v[46:49], v[146:149], v[178:181], v[46:49]
	v_mfma_f32_16x16x32_bf16 v[46:49], v[150:153], v[184:187], v[46:49]
	v_mfma_f32_16x16x32_bf16 v[38:41], v[146:149], v[220:223], v[38:41]
	v_mfma_f32_16x16x32_bf16 v[38:41], v[150:153], v[224:227], v[38:41]
	v_mfma_f32_16x16x32_bf16 v[42:45], v[154:157], v[220:223], v[42:45]
	v_mfma_f32_16x16x32_bf16 v[42:45], v[158:161], v[224:227], v[42:45]
	v_mfma_f32_16x16x32_bf16 v[34:37], v[154:157], v[178:181], v[34:37]
	v_mfma_f32_16x16x32_bf16 v[34:37], v[158:161], v[184:187], v[34:37]
	v_mfma_f32_16x16x32_bf16 v[2:5], v[154:157], v[170:173], v[2:5]
	v_mfma_f32_16x16x32_bf16 v[2:5], v[158:161], v[174:177], v[2:5]
	v_mfma_f32_16x16x32_bf16 v[6:9], v[154:157], v[162:165], v[6:9]
	v_mfma_f32_16x16x32_bf16 v[6:9], v[158:161], v[166:169], v[6:9]
	s_barrier
	s_setprio 0
	s_add_i32 s0, s0, 2
	s_add_u32 s66, s66, 0x100
	s_addc_u32 s67, s67, 0
	s_cmp_gt_u32 s0, 29
	s_mov_b64 s[12:13], s[96:97]
	s_cbranch_scc0 .LBB0_1327
	s_and_b64 vcc, exec, s[78:79]
	s_cbranch_vccz .LBB0_1330
	s_barrier

; #define PG8_STAGE(bufoff, gbase, voff) do { _Pragma("unroll") for (int _i = 0; _i < 2; ++_i) \
;         __builtin_amdgcn_global_load_lds((const unsigned*)((const char*)(gbase) + (voff)[_i]), (PG8_LAS unsigned*)(lds + (bufoff) + ldsw + _i * 8192), 16, 0, 0); } while (0)
; #define PG8_LDA(dst, b, h) do { _Pragma("unroll") for (int m = 0; m < 4; ++m) _Pragma("unroll") for (int k = 0; k < 2; ++k) dst[m][k] = *(const PG8_LAS bf16x8*)(lds + PG8_SA(b, h) + aoff + m * 2048 + k * 1024); } while (0)
; #define PG8_LDB(dst, b, h) do { _Pragma("unroll") for (int n = 0; n < 2; ++n) _Pragma("unroll") for (int k = 0; k < 2; ++k) dst[n][k] = *(const PG8_LAS bf16x8*)(lds + PG8_SB(b, h) + boff + n * 2048 + k * 1024); } while (0)
; #define PG8_WAIT_L(n) asm volatile("s_waitcnt lgkmcnt(" #n ")" ::: "memory")
; #define PG8_WAIT_V_SEL(sel) asm volatile("s_cmp_eq_u32 %0, 0\n\ts_cbranch_scc1 .Lw8_%=\n\ts_waitcnt vmcnt(22)\n\ts_branch .Lwd_%=\n.Lw8_%=:\n\ts_waitcnt vmcnt(8)\n.Lwd_%=:" :: "s"(sel) : "memory", "scc")
; #define PG8_BAR __builtin_amdgcn_s_barrier()
; #define PG8_SCHED __builtin_amdgcn_sched_barrier(0)
;     ...
;         for (int t = 0; t < nt * KREP; t += 2) {
;             const bool last = (t == nt * KREP - 2);
;             const int t1w = KREP > 1 ? ((t + 1) & (nt - 1)) : t + 1, t2w = KREP > 1 ? ((t + 2) & (nt - 1)) : t + 2;
;             const char* a1 = cA + (size_t)t1w * kstep;
;             const char* a2 = last ? nA : cA + (size_t)t2w * kstep; const char* b2 = last ? nB : cB + (size_t)t2w * kstep;
;             const char* a3 = a2 + kstep; const char* b3 = b2 + kstep;
;             if (last && has_next) S.a_ready(nxt);
;             const int relax = __builtin_amdgcn_readfirstlane((MK_RELAXW && t == 0 && ui > 0) ? 1 : 0);
;             if constexpr (SP2) {
;             PG8_LDB(B0, 0, 0); PG8_LDB(B1, 0, 1); PG8_SCHED; PG8_LDA(At, 0, 0); PG8_STAGE(PG8_SA(1, 1), a1 + hstep, voffA);
;             PG8_WAIT_V_SEL(relax);
;             PG8_WAIT_L(0); PG8_BAR; PG8_MMA(0, 0, At, B0); PG8_MMA(0, 1, At, B1); PG8_BAR; PG8_SCHED;
;             PG8_LDA(At, 0, 1); PG8_STAGE(PG8_SB(0, 0), b2, voffB); PG8_STAGE(PG8_SB(0, 1), b2 + hstep, voffB); PG8_STAGE(PG8_SA(0, 0), a2, voffA);
;             PG8_WAIT_V_SEL(relax);
;             PG8_WAIT_L(0); PG8_BAR; PG8_MMA(1, 0, At, B0); PG8_MMA(1, 1, At, B1); PG8_BAR; PG8_SCHED;
.LBB0_1648:
	s_add_u32 s10, s8, 0x100
	s_addc_u32 s11, s9, 0
	s_add_i32 s46, 0, 0x10000
	s_cmpk_eq_i32 s45, 0x52
	s_cselect_b32 s41, s1, s11
	s_cselect_b32 s40, s0, s10
	s_cselect_b32 s81, s79, s44
	s_cselect_b32 s80, s78, s37
	s_add_i32 s47, 0, 0x14000
	ds_read_b128 v[58:61], v206
	ds_read_b128 v[62:65], v206 offset:1024
	ds_read_b128 v[74:77], v206 offset:2048
	ds_read_b128 v[78:81], v206 offset:3072
	ds_read_b128 v[130:133], v206 offset:16384
	ds_read_b128 v[142:145], v206 offset:17408
	ds_read_b128 v[154:157], v206 offset:18432
	ds_read_b128 v[158:161], v206 offset:19456
	s_add_i32 m0, s91, 0xc000
	ds_read_b128 v[162:165], v246
	ds_read_b128 v[166:169], v246 offset:1024
	ds_read_b128 v[170:173], v246 offset:2048
	ds_read_b128 v[174:177], v246 offset:3072
	ds_read_b128 v[184:187], v246 offset:4096
	ds_read_b128 v[194:197], v246 offset:5120
	ds_read_b128 v[198:201], v246 offset:6144
	ds_read_b128 v[202:205], v246 offset:7168
	global_load_lds_dwordx4 v190, s[8:9]
	s_add_i32 m0, s91, 0xe000
	s_nop 0
	global_load_lds_dwordx4 v192, s[8:9]
	s_waitcnt vmcnt(8)
	s_waitcnt lgkmcnt(0)
	s_setprio 1
	s_barrier
	v_mfma_f32_16x16x32_bf16 v[150:153], v[58:61], v[162:165], v[150:153]
	v_mfma_f32_16x16x32_bf16 v[150:153], v[62:65], v[166:169], v[150:153]
	v_mfma_f32_16x16x32_bf16 v[126:129], v[58:61], v[170:173], v[126:129]
	v_mfma_f32_16x16x32_bf16 v[126:129], v[62:65], v[174:177], v[126:129]
	v_mfma_f32_16x16x32_bf16 v[110:113], v[58:61], v[184:187], v[110:113]
	v_mfma_f32_16x16x32_bf16 v[110:113], v[62:65], v[194:197], v[110:113]
	v_mfma_f32_16x16x32_bf16 v[94:97], v[58:61], v[198:201], v[94:97]
	v_mfma_f32_16x16x32_bf16 v[94:97], v[62:65], v[202:205], v[94:97]
	v_mfma_f32_16x16x32_bf16 v[90:93], v[74:77], v[198:201], v[90:93]
	v_mfma_f32_16x16x32_bf16 v[90:93], v[78:81], v[202:205], v[90:93]
	v_mfma_f32_16x16x32_bf16 v[106:109], v[74:77], v[184:187], v[106:109]
	v_mfma_f32_16x16x32_bf16 v[106:109], v[78:81], v[194:197], v[106:109]
	v_mfma_f32_16x16x32_bf16 v[122:125], v[74:77], v[170:173], v[122:125]
	v_mfma_f32_16x16x32_bf16 v[122:125], v[78:81], v[174:177], v[122:125]
	v_mfma_f32_16x16x32_bf16 v[146:149], v[74:77], v[162:165], v[146:149]
	v_mfma_f32_16x16x32_bf16 v[146:149], v[78:81], v[166:169], v[146:149]
	v_mfma_f32_16x16x32_bf16 v[138:141], v[130:133], v[162:165], v[138:141]
	v_mfma_f32_16x16x32_bf16 v[138:141], v[142:145], v[166:169], v[138:141]
	v_mfma_f32_16x16x32_bf16 v[118:121], v[130:133], v[170:173], v[118:121]
	v_mfma_f32_16x16x32_bf16 v[118:121], v[142:145], v[174:177], v[118:121]
	v_mfma_f32_16x16x32_bf16 v[102:105], v[130:133], v[184:187], v[102:105]
	v_mfma_f32_16x16x32_bf16 v[102:105], v[142:145], v[194:197], v[102:105]
	v_mfma_f32_16x16x32_bf16 v[86:89], v[130:133], v[198:201], v[86:89]
	v_mfma_f32_16x16x32_bf16 v[86:89], v[142:145], v[202:205], v[86:89]
	v_mfma_f32_16x16x32_bf16 v[82:85], v[154:157], v[198:201], v[82:85]
	v_mfma_f32_16x16x32_bf16 v[82:85], v[158:161], v[202:205], v[82:85]
	v_mfma_f32_16x16x32_bf16 v[98:101], v[154:157], v[184:187], v[98:101]
	v_mfma_f32_16x16x32_bf16 v[98:101], v[158:161], v[194:197], v[98:101]
	v_mfma_f32_16x16x32_bf16 v[114:117], v[154:157], v[170:173], v[114:117]
	v_mfma_f32_16x16x32_bf16 v[114:117], v[158:161], v[174:177], v[114:117]
	v_mfma_f32_16x16x32_bf16 v[134:137], v[154:157], v[162:165], v[134:137]
	v_mfma_f32_16x16x32_bf16 v[134:137], v[158:161], v[166:169], v[134:137]
	s_barrier
	s_setprio 0
	s_add_i32 s8, s46, s90
	s_mov_b32 m0, s8
	ds_read_b128 v[162:165], v246 offset:16384
	ds_read_b128 v[166:169], v246 offset:17408
	ds_read_b128 v[170:173], v246 offset:18432
	ds_read_b128 v[174:177], v246 offset:19456
	ds_read_b128 v[184:187], v246 offset:20480
	ds_read_b128 v[194:197], v246 offset:21504
	ds_read_b128 v[198:201], v246 offset:22528
	ds_read_b128 v[202:205], v246 offset:23552
	global_load_lds_dwordx4 v182, s[80:81]
	s_add_i32 m0, s8, 0x2000
	s_add_u32 s8, s80, 0x158000
	s_addc_u32 s9, s81, 0
	s_add_i32 s46, s47, s90
	global_load_lds_dwordx4 v188, s[80:81]
	s_mov_b32 m0, s46
	s_nop 0
	global_load_lds_dwordx4 v182, s[8:9]
	s_add_i32 m0, s46, 0x2000
	s_nop 0
	global_load_lds_dwordx4 v188, s[8:9]
	s_mov_b32 m0, s91
	s_nop 0
	global_load_lds_dwordx4 v178, s[40:41]
	s_mov_b32 m0, s92
	s_nop 0
	global_load_lds_dwordx4 v180, s[40:41]
	s_waitcnt vmcnt(8)
	s_waitcnt lgkmcnt(0)
	s_setprio 1
	s_barrier
	v_mfma_f32_16x16x32_bf16 v[70:73], v[58:61], v[162:165], v[70:73]
	v_mfma_f32_16x16x32_bf16 v[70:73], v[62:65], v[166:169], v[70:73]
	v_mfma_f32_16x16x32_bf16 v[46:49], v[58:61], v[170:173], v[46:49]
	v_mfma_f32_16x16x32_bf16 v[46:49], v[62:65], v[174:177], v[46:49]
	v_mfma_f32_16x16x32_bf16 v[30:33], v[58:61], v[184:187], v[30:33]
	v_mfma_f32_16x16x32_bf16 v[30:33], v[62:65], v[194:197], v[30:33]
	v_mfma_f32_16x16x32_bf16 v[14:17], v[58:61], v[198:201], v[14:17]
	v_mfma_f32_16x16x32_bf16 v[14:17], v[62:65], v[202:205], v[14:17]
	v_mfma_f32_16x16x32_bf16 v[10:13], v[74:77], v[198:201], v[10:13]
	v_mfma_f32_16x16x32_bf16 v[10:13], v[78:81], v[202:205], v[10:13]
	v_mfma_f32_16x16x32_bf16 v[26:29], v[74:77], v[184:187], v[26:29]
	v_mfma_f32_16x16x32_bf16 v[26:29], v[78:81], v[194:197], v[26:29]
	v_mfma_f32_16x16x32_bf16 v[42:45], v[74:77], v[170:173], v[42:45]
	v_mfma_f32_16x16x32_bf16 v[42:45], v[78:81], v[174:177], v[42:45]
	v_mfma_f32_16x16x32_bf16 v[66:69], v[74:77], v[162:165], v[66:69]
	v_mfma_f32_16x16x32_bf16 v[66:69], v[78:81], v[166:169], v[66:69]
	v_mfma_f32_16x16x32_bf16 v[54:57], v[130:133], v[162:165], v[54:57]
	v_mfma_f32_16x16x32_bf16 v[54:57], v[142:145], v[166:169], v[54:57]
	v_mfma_f32_16x16x32_bf16 v[38:41], v[130:133], v[170:173], v[38:41]
	v_mfma_f32_16x16x32_bf16 v[38:41], v[142:145], v[174:177], v[38:41]
	v_mfma_f32_16x16x32_bf16 v[22:25], v[130:133], v[184:187], v[22:25]
	v_mfma_f32_16x16x32_bf16 v[22:25], v[142:145], v[194:197], v[22:25]
	v_mfma_f32_16x16x32_bf16 v[6:9], v[130:133], v[198:201], v[6:9]
	v_mfma_f32_16x16x32_bf16 v[6:9], v[142:145], v[202:205], v[6:9]
	v_mfma_f32_16x16x32_bf16 v[2:5], v[154:157], v[198:201], v[2:5]
	v_mfma_f32_16x16x32_bf16 v[2:5], v[158:161], v[202:205], v[2:5]
	v_mfma_f32_16x16x32_bf16 v[18:21], v[154:157], v[184:187], v[18:21]
	v_mfma_f32_16x16x32_bf16 v[18:21], v[158:161], v[194:197], v[18:21]
	v_mfma_f32_16x16x32_bf16 v[34:37], v[154:157], v[170:173], v[34:37]
	v_mfma_f32_16x16x32_bf16 v[34:37], v[158:161], v[174:177], v[34:37]
	v_mfma_f32_16x16x32_bf16 v[50:53], v[154:157], v[162:165], v[50:53]
	v_mfma_f32_16x16x32_bf16 v[50:53], v[158:161], v[166:169], v[50:53]
	s_barrier
; #define PG8_STAGE(bufoff, gbase, voff) do { _Pragma("unroll") for (int _i = 0; _i < 2; ++_i) \
;         __builtin_amdgcn_global_load_lds((const unsigned*)((const char*)(gbase) + (voff)[_i]), (PG8_LAS unsigned*)(lds + (bufoff) + ldsw + _i * 8192), 16, 0, 0); } while (0)
; #define PG8_LDA(dst, b, h) do { _Pragma("unroll") for (int m = 0; m < 4; ++m) _Pragma("unroll") for (int k = 0; k < 2; ++k) dst[m][k] = *(const PG8_LAS bf16x8*)(lds + PG8_SA(b, h) + aoff + m * 2048 + k * 1024); } while (0)
; #define PG8_LDB(dst, b, h) do { _Pragma("unroll") for (int n = 0; n < 2; ++n) _Pragma("unroll") for (int k = 0; k < 2; ++k) dst[n][k] = *(const PG8_LAS bf16x8*)(lds + PG8_SB(b, h) + boff + n * 2048 + k * 1024); } while (0)
; #define PG8_WAIT_V(n) asm volatile("s_waitcnt vmcnt(" #n ")" ::: "memory")
; #define PG8_WAIT_L(n) asm volatile("s_waitcnt lgkmcnt(" #n ")" ::: "memory")
; #define PG8_BAR __builtin_amdgcn_s_barrier()
; #define PG8_SCHED __builtin_amdgcn_sched_barrier(0)
;     ...
;             PG8_LDB(B0, 1, 0); PG8_LDB(B1, 1, 1); PG8_SCHED; PG8_LDA(At, 1, 0); PG8_STAGE(PG8_SA(0, 1), a2 + hstep, voffA);
;             PG8_WAIT_V(8); PG8_WAIT_L(0); PG8_BAR; PG8_MMA(0, 0, At, B0); PG8_MMA(0, 1, At, B1); PG8_BAR; PG8_SCHED;
;             PG8_LDA(At, 1, 1); PG8_STAGE(PG8_SB(1, 0), b3, voffB); PG8_STAGE(PG8_SB(1, 1), b3 + hstep, voffB); PG8_STAGE(PG8_SA(1, 0), a3, voffA);
;             PG8_WAIT_V(8); PG8_WAIT_L(0); PG8_BAR; PG8_MMA(1, 0, At, B0); PG8_MMA(1, 1, At, B1); PG8_BAR; PG8_SCHED;
;     ...
;         if constexpr (ALIGN_EPI) { if (wr == 0) PG8_BAR; }
	s_setprio 0
	s_add_i32 s46, 0, 0x18000
	s_add_i32 s47, 0, 0x1c000
	ds_read_b128 v[58:61], v206 offset:32768
	ds_read_b128 v[62:65], v206 offset:33792
	ds_read_b128 v[74:77], v206 offset:34816
	ds_read_b128 v[78:81], v206 offset:35840
	ds_read_b128 v[130:133], v206 offset:49152
	ds_read_b128 v[142:145], v206 offset:50176
	ds_read_b128 v[154:157], v206 offset:51200
	ds_read_b128 v[158:161], v206 offset:52224
	s_add_u32 s8, s40, 0x158000
	s_addc_u32 s9, s41, 0
	s_mov_b32 m0, s93
	ds_read_b128 v[162:165], v246 offset:32768
	ds_read_b128 v[166:169], v246 offset:33792
	ds_read_b128 v[170:173], v246 offset:34816
	ds_read_b128 v[174:177], v246 offset:35840
	ds_read_b128 v[184:187], v246 offset:36864
	ds_read_b128 v[194:197], v246 offset:37888
	ds_read_b128 v[198:201], v246 offset:38912
	ds_read_b128 v[202:205], v246 offset:39936
	global_load_lds_dwordx4 v178, s[8:9]
	s_mov_b32 m0, s94
	s_nop 0
	global_load_lds_dwordx4 v180, s[8:9]
	s_waitcnt vmcnt(8)
	s_waitcnt lgkmcnt(0)
	s_setprio 1
	s_barrier
	v_mfma_f32_16x16x32_bf16 v[150:153], v[58:61], v[162:165], v[150:153]
	v_mfma_f32_16x16x32_bf16 v[150:153], v[62:65], v[166:169], v[150:153]
	v_mfma_f32_16x16x32_bf16 v[126:129], v[58:61], v[170:173], v[126:129]
	v_mfma_f32_16x16x32_bf16 v[126:129], v[62:65], v[174:177], v[126:129]
	v_mfma_f32_16x16x32_bf16 v[110:113], v[58:61], v[184:187], v[110:113]
	v_mfma_f32_16x16x32_bf16 v[110:113], v[62:65], v[194:197], v[110:113]
	v_mfma_f32_16x16x32_bf16 v[94:97], v[58:61], v[198:201], v[94:97]
	v_mfma_f32_16x16x32_bf16 v[94:97], v[62:65], v[202:205], v[94:97]
	v_mfma_f32_16x16x32_bf16 v[90:93], v[74:77], v[198:201], v[90:93]
	v_mfma_f32_16x16x32_bf16 v[90:93], v[78:81], v[202:205], v[90:93]
	v_mfma_f32_16x16x32_bf16 v[106:109], v[74:77], v[184:187], v[106:109]
	v_mfma_f32_16x16x32_bf16 v[106:109], v[78:81], v[194:197], v[106:109]
	v_mfma_f32_16x16x32_bf16 v[122:125], v[74:77], v[170:173], v[122:125]
	v_mfma_f32_16x16x32_bf16 v[122:125], v[78:81], v[174:177], v[122:125]
	v_mfma_f32_16x16x32_bf16 v[146:149], v[74:77], v[162:165], v[146:149]
	v_mfma_f32_16x16x32_bf16 v[146:149], v[78:81], v[166:169], v[146:149]
	v_mfma_f32_16x16x32_bf16 v[138:141], v[130:133], v[162:165], v[138:141]
	v_mfma_f32_16x16x32_bf16 v[138:141], v[142:145], v[166:169], v[138:141]
	v_mfma_f32_16x16x32_bf16 v[118:121], v[130:133], v[170:173], v[118:121]
	v_mfma_f32_16x16x32_bf16 v[118:121], v[142:145], v[174:177], v[118:121]
	v_mfma_f32_16x16x32_bf16 v[102:105], v[130:133], v[184:187], v[102:105]
	v_mfma_f32_16x16x32_bf16 v[102:105], v[142:145], v[194:197], v[102:105]
	v_mfma_f32_16x16x32_bf16 v[86:89], v[130:133], v[198:201], v[86:89]
	v_mfma_f32_16x16x32_bf16 v[86:89], v[142:145], v[202:205], v[86:89]
	v_mfma_f32_16x16x32_bf16 v[82:85], v[154:157], v[198:201], v[82:85]
	v_mfma_f32_16x16x32_bf16 v[82:85], v[158:161], v[202:205], v[82:85]
	v_mfma_f32_16x16x32_bf16 v[98:101], v[154:157], v[184:187], v[98:101]
	v_mfma_f32_16x16x32_bf16 v[98:101], v[158:161], v[194:197], v[98:101]
	v_mfma_f32_16x16x32_bf16 v[114:117], v[154:157], v[170:173], v[114:117]
	v_mfma_f32_16x16x32_bf16 v[114:117], v[158:161], v[174:177], v[114:117]
	v_mfma_f32_16x16x32_bf16 v[134:137], v[154:157], v[162:165], v[134:137]
	v_mfma_f32_16x16x32_bf16 v[134:137], v[158:161], v[166:169], v[134:137]
	s_barrier
	s_setprio 0
	s_add_i32 s8, s46, s90
	s_mov_b32 m0, s8
	ds_read_b128 v[162:165], v246 offset:49152
	ds_read_b128 v[166:169], v246 offset:50176
	ds_read_b128 v[170:173], v246 offset:51200
	ds_read_b128 v[174:177], v246 offset:52224
	ds_read_b128 v[184:187], v246 offset:53248
	ds_read_b128 v[194:197], v246 offset:54272
	ds_read_b128 v[198:201], v246 offset:55296
	ds_read_b128 v[202:205], v246 offset:56320
	s_add_u32 s100, s80, 0x80
	s_addc_u32 s101, s81, 0
	global_load_lds_dwordx4 v182, s[100:101]
	s_add_i32 m0, s8, 0x2000
	s_add_u32 s8, s80, 0x158080
	s_addc_u32 s9, s81, 0
	s_add_i32 vcc_lo, s47, s90
	global_load_lds_dwordx4 v188, s[100:101]
	s_mov_b32 m0, vcc_lo
	s_nop 0
	global_load_lds_dwordx4 v182, s[8:9]
	s_add_i32 m0, vcc_lo, 0x2000
	s_nop 0
	global_load_lds_dwordx4 v188, s[8:9]
	s_mov_b32 m0, s31
	s_nop 0
	s_add_u32 s100, s40, 0x80
	s_addc_u32 s101, s41, 0
	global_load_lds_dwordx4 v178, s[100:101]
	s_mov_b32 m0, s56
	s_nop 0
	global_load_lds_dwordx4 v180, s[100:101]
	s_waitcnt vmcnt(8)
	s_waitcnt lgkmcnt(0)
	s_setprio 1
	s_barrier
	v_mfma_f32_16x16x32_bf16 v[70:73], v[58:61], v[162:165], v[70:73]
	v_mfma_f32_16x16x32_bf16 v[70:73], v[62:65], v[166:169], v[70:73]
	v_mfma_f32_16x16x32_bf16 v[46:49], v[58:61], v[170:173], v[46:49]
	v_mfma_f32_16x16x32_bf16 v[46:49], v[62:65], v[174:177], v[46:49]
	v_mfma_f32_16x16x32_bf16 v[30:33], v[58:61], v[184:187], v[30:33]
	v_mfma_f32_16x16x32_bf16 v[30:33], v[62:65], v[194:197], v[30:33]
	v_mfma_f32_16x16x32_bf16 v[14:17], v[58:61], v[198:201], v[14:17]
	v_mfma_f32_16x16x32_bf16 v[14:17], v[62:65], v[202:205], v[14:17]
	v_mfma_f32_16x16x32_bf16 v[10:13], v[74:77], v[198:201], v[10:13]
	v_mfma_f32_16x16x32_bf16 v[10:13], v[78:81], v[202:205], v[10:13]
	v_mfma_f32_16x16x32_bf16 v[26:29], v[74:77], v[184:187], v[26:29]
	v_mfma_f32_16x16x32_bf16 v[26:29], v[78:81], v[194:197], v[26:29]
	v_mfma_f32_16x16x32_bf16 v[42:45], v[74:77], v[170:173], v[42:45]
	v_mfma_f32_16x16x32_bf16 v[42:45], v[78:81], v[174:177], v[42:45]
	v_mfma_f32_16x16x32_bf16 v[66:69], v[74:77], v[162:165], v[66:69]
	v_mfma_f32_16x16x32_bf16 v[66:69], v[78:81], v[166:169], v[66:69]
	v_mfma_f32_16x16x32_bf16 v[54:57], v[130:133], v[162:165], v[54:57]
	v_mfma_f32_16x16x32_bf16 v[54:57], v[142:145], v[166:169], v[54:57]
	v_mfma_f32_16x16x32_bf16 v[38:41], v[130:133], v[170:173], v[38:41]
	v_mfma_f32_16x16x32_bf16 v[38:41], v[142:145], v[174:177], v[38:41]
	v_mfma_f32_16x16x32_bf16 v[22:25], v[130:133], v[184:187], v[22:25]
	v_mfma_f32_16x16x32_bf16 v[22:25], v[142:145], v[194:197], v[22:25]
	v_mfma_f32_16x16x32_bf16 v[6:9], v[130:133], v[198:201], v[6:9]
	v_mfma_f32_16x16x32_bf16 v[6:9], v[142:145], v[202:205], v[6:9]
	v_mfma_f32_16x16x32_bf16 v[2:5], v[154:157], v[198:201], v[2:5]
	v_mfma_f32_16x16x32_bf16 v[2:5], v[158:161], v[202:205], v[2:5]
	v_mfma_f32_16x16x32_bf16 v[18:21], v[154:157], v[184:187], v[18:21]
	v_mfma_f32_16x16x32_bf16 v[18:21], v[158:161], v[194:197], v[18:21]
	v_mfma_f32_16x16x32_bf16 v[34:37], v[154:157], v[170:173], v[34:37]
	v_mfma_f32_16x16x32_bf16 v[34:37], v[158:161], v[174:177], v[34:37]
	v_mfma_f32_16x16x32_bf16 v[50:53], v[154:157], v[162:165], v[50:53]
	v_mfma_f32_16x16x32_bf16 v[50:53], v[158:161], v[166:169], v[50:53]
	s_barrier
	s_setprio 0
	s_add_i32 s45, s45, 2
	s_add_u32 s37, s37, 0x100
	s_addc_u32 s44, s44, 0
	s_cmpk_gt_u32 s45, 0x53
	s_mov_b64 s[8:9], s[10:11]
	s_cbranch_scc0 .LBB0_1648
	s_and_b64 vcc, exec, s[76:77]
	s_cbranch_vccz .LBB0_1651
	s_barrier
